# swa_item qt loop rewritten: pipelined LDS reads for QK/PV, q prefetch, counted waits
# speedup vs baseline: 1.0124x; 1.0078x over previous
.LBB0_149:
	s_or_b64 exec, exec, s[38:39]
	s_waitcnt vmcnt(0) lgkmcnt(0)
	ds_write_b128 v83, v[2:5]
	v_add_u32_e32 v2, v69, v49
	ds_write_b16 v2, v6 offset:36864
	ds_write_b16_d16_hi v70, v6 offset:37392
	ds_write_b16 v2, v7 offset:37920
	ds_write_b16_d16_hi v70, v7 offset:38448
	v_add_u32_e32 v2, v69, v55
	ds_write_b16 v2, v8 offset:36864
	ds_write_b16_d16_hi v71, v8 offset:37392
	v_add_u32_e32 v2, v69, v57
	ds_write_b16 v2, v9 offset:36864
	ds_write_b16_d16_hi v72, v9 offset:37392
	v_lshl_add_u32 v2, s15, 3, v181
	v_ashrrev_i32_e32 v3, 31, v2
	v_lshl_add_u64 v[4:5], v[2:3], 2, s[20:21]
	s_waitcnt lgkmcnt(0)
	s_barrier
	global_load_dword v85, v[4:5], off
	v_lshlrev_b32_e32 v22, 6, v2
	v_or_b32_e32 v4, s78, v44
	v_mov_b64_e32 v[2:3], s[26:27]
	s_mul_i32 s15, s79, 0x4200
	v_mad_u64_u32 v[2:3], s[8:9], v4, s83, v[2:3]
	v_ashrrev_i32_e32 v23, 31, v22
	v_add_u32_e32 v3, s15, v3
	v_lshl_add_u64 v[2:3], v[22:23], 1, v[2:3]
	v_lshl_add_u64 v[2:3], v[2:3], 0, v[0:1]
	s_mov_b64 s[18:19], 0x1800
	s_movk_i32 s8, 0x1000
	v_lshl_add_u64 v[24:25], v[2:3], 0, s[18:19]
	v_add_u32_e32 v118, v35, v73
	v_and_b32_e32 v248, 15, v195
	v_bfe_u32 v249, v195, 4, 2
	v_mul_u32_u24_e32 v245, 0x210, v248
	v_lshl_add_u32 v245, v249, 3, v245
	v_add_u32_e32 v245, 0x9000, v245
	v_lshlrev_b32_e32 v249, 2, v249
	v_mov_b64_e32 v[246:247], v[24:25]
	s_mov_b64 s[8:9], 0x42000
	global_load_dwordx4 v[90:93], v[246:247], off
	global_load_dwordx4 v[94:97], v[246:247], off offset:64
	s_waitcnt vmcnt(0)
	ds_read_b128 v[106:109], v118
	ds_read_b128 v[110:113], v118 offset:64
	ds_read_b128 v[114:117], v118 offset:2304
	ds_read_b128 v[128:131], v118 offset:2368
	ds_read_b128 v[132:135], v118 offset:4608
	ds_read_b128 v[120:123], v118 offset:4672
	s_waitcnt lgkmcnt(5)
	v_mfma_f32_16x16x32_bf16 v[2:5], v[106:109], v[90:93], 0
	ds_read_b128 v[106:109], v118 offset:6912
	s_waitcnt lgkmcnt(5)
	v_mfma_f32_16x16x32_bf16 v[2:5], v[110:113], v[94:97], v[2:5]
	ds_read_b128 v[110:113], v118 offset:6976
	s_waitcnt lgkmcnt(5)
	v_mfma_f32_16x16x32_bf16 v[6:9], v[114:117], v[90:93], 0
	ds_read_b128 v[114:117], v118 offset:9216
	s_waitcnt lgkmcnt(5)
	v_mfma_f32_16x16x32_bf16 v[6:9], v[128:131], v[94:97], v[6:9]
	ds_read_b128 v[128:131], v118 offset:9280
	s_waitcnt lgkmcnt(5)
	v_mfma_f32_16x16x32_bf16 v[10:13], v[132:135], v[90:93], 0
	ds_read_b128 v[132:135], v118 offset:11520
	s_waitcnt lgkmcnt(5)
	v_mfma_f32_16x16x32_bf16 v[10:13], v[120:123], v[94:97], v[10:13]
	ds_read_b128 v[120:123], v118 offset:11584
	s_waitcnt lgkmcnt(5)
	v_mfma_f32_16x16x32_bf16 v[14:17], v[106:109], v[90:93], 0
	ds_read_b128 v[106:109], v118 offset:13824
	s_waitcnt lgkmcnt(5)
	v_mfma_f32_16x16x32_bf16 v[14:17], v[110:113], v[94:97], v[14:17]
	ds_read_b128 v[110:113], v118 offset:13888
	s_waitcnt lgkmcnt(5)
	v_mfma_f32_16x16x32_bf16 v[18:21], v[114:117], v[90:93], 0
	ds_read_b128 v[114:117], v118 offset:16128
	s_waitcnt lgkmcnt(5)
	v_mfma_f32_16x16x32_bf16 v[18:21], v[128:131], v[94:97], v[18:21]
	ds_read_b128 v[128:131], v118 offset:16192
	s_waitcnt lgkmcnt(5)
	v_mfma_f32_16x16x32_bf16 v[22:25], v[132:135], v[90:93], 0
	ds_read_b128 v[132:135], v118 offset:18432
	s_waitcnt lgkmcnt(5)
	v_mfma_f32_16x16x32_bf16 v[22:25], v[120:123], v[94:97], v[22:25]
	ds_read_b128 v[120:123], v118 offset:18496
	s_waitcnt lgkmcnt(5)
	v_mfma_f32_16x16x32_bf16 v[26:29], v[106:109], v[90:93], 0
	s_waitcnt lgkmcnt(4)
	v_mfma_f32_16x16x32_bf16 v[26:29], v[110:113], v[94:97], v[26:29]
	s_waitcnt lgkmcnt(3)
	v_mfma_f32_16x16x32_bf16 v[30:33], v[114:117], v[90:93], 0
	s_waitcnt lgkmcnt(2)
	v_mfma_f32_16x16x32_bf16 v[30:33], v[128:131], v[94:97], v[30:33]
	s_waitcnt lgkmcnt(1)
	v_mfma_f32_16x16x32_bf16 v[86:89], v[132:135], v[90:93], 0
	s_waitcnt lgkmcnt(0)
	v_mfma_f32_16x16x32_bf16 v[86:89], v[120:123], v[94:97], v[86:89]
	v_lshl_add_u64 v[240:241], v[246:247], 0, s[8:9]
	global_load_dwordx4 v[98:101], v[240:241], off
	global_load_dwordx4 v[102:105], v[240:241], off offset:64
	v_add_u32_e32 v242, 0, v249
	v_cmp_gt_u32_e32 vcc, v242, v248
	s_nop 1
	s_and_b64 vcc, vcc, s[66:67]
	s_nop 0
	v_cndmask_b32_e32 v2, v205, v2, vcc
	v_add_u32_e32 v242, 1, v249
	v_cmp_gt_u32_e32 vcc, v242, v248
	s_nop 1
	s_and_b64 vcc, vcc, s[66:67]
	s_nop 0
	v_cndmask_b32_e32 v3, v205, v3, vcc
	v_add_u32_e32 v242, 2, v249
	v_cmp_gt_u32_e32 vcc, v242, v248
	s_nop 1
	s_and_b64 vcc, vcc, s[66:67]
	s_nop 0
	v_cndmask_b32_e32 v4, v205, v4, vcc
	v_add_u32_e32 v242, 3, v249
	v_cmp_gt_u32_e32 vcc, v242, v248
	s_nop 1
	s_and_b64 vcc, vcc, s[66:67]
	s_nop 0
	v_cndmask_b32_e32 v5, v205, v5, vcc
	v_cndmask_b32_e64 v6, v205, v6, s[66:67]
	v_cndmask_b32_e64 v7, v205, v7, s[66:67]
	v_cndmask_b32_e64 v8, v205, v8, s[66:67]
	v_cndmask_b32_e64 v9, v205, v9, s[66:67]
	v_cndmask_b32_e64 v10, v205, v10, s[66:67]
	v_cndmask_b32_e64 v11, v205, v11, s[66:67]
	v_cndmask_b32_e64 v12, v205, v12, s[66:67]
	v_cndmask_b32_e64 v13, v205, v13, s[66:67]
	v_cndmask_b32_e64 v14, v205, v14, s[66:67]
	v_cndmask_b32_e64 v15, v205, v15, s[66:67]
	v_cndmask_b32_e64 v16, v205, v16, s[66:67]
	v_cndmask_b32_e64 v17, v205, v17, s[66:67]
	v_cndmask_b32_e64 v18, v205, v18, s[66:67]
	v_cndmask_b32_e64 v19, v205, v19, s[66:67]
	v_cndmask_b32_e64 v20, v205, v20, s[66:67]
	v_cndmask_b32_e64 v21, v205, v21, s[66:67]
	v_cndmask_b32_e64 v22, v205, v22, s[66:67]
	v_cndmask_b32_e64 v23, v205, v23, s[66:67]
	v_cndmask_b32_e64 v24, v205, v24, s[66:67]
	v_cndmask_b32_e64 v25, v205, v25, s[66:67]
	v_cndmask_b32_e64 v26, v205, v26, s[66:67]
	v_cndmask_b32_e64 v27, v205, v27, s[66:67]
	v_cndmask_b32_e64 v28, v205, v28, s[66:67]
	v_cndmask_b32_e64 v29, v205, v29, s[66:67]
	v_cndmask_b32_e64 v30, v205, v30, s[66:67]
	v_cndmask_b32_e64 v31, v205, v31, s[66:67]
	v_cndmask_b32_e64 v32, v205, v32, s[66:67]
	v_cndmask_b32_e64 v33, v205, v33, s[66:67]
	v_add_u32_e32 v242, 0, v249
	v_cmp_le_u32_e32 vcc, v242, v248
	s_nop 1
	v_cndmask_b32_e32 v86, v205, v86, vcc
	v_add_u32_e32 v242, 1, v249
	v_cmp_le_u32_e32 vcc, v242, v248
	s_nop 1
	v_cndmask_b32_e32 v87, v205, v87, vcc
	v_add_u32_e32 v242, 2, v249
	v_cmp_le_u32_e32 vcc, v242, v248
	s_nop 1
	v_cndmask_b32_e32 v88, v205, v88, vcc
	v_add_u32_e32 v242, 3, v249
	v_cmp_le_u32_e32 vcc, v242, v248
	s_nop 1
	v_cndmask_b32_e32 v89, v205, v89, vcc
	v_max3_f32 v238, v2, v3, v205
	v_max3_f32 v238, v238, v4, v5
	v_max3_f32 v238, v238, v6, v7
	v_max3_f32 v238, v238, v8, v9
	v_max3_f32 v238, v238, v10, v11
	v_max3_f32 v238, v238, v12, v13
	v_max3_f32 v238, v238, v14, v15
	v_max3_f32 v238, v238, v16, v17
	v_max3_f32 v238, v238, v18, v19
	v_max3_f32 v238, v238, v20, v21
	v_max3_f32 v238, v238, v22, v23
	v_max3_f32 v238, v238, v24, v25
	v_max3_f32 v238, v238, v26, v27
	v_max3_f32 v238, v238, v28, v29
	v_max3_f32 v238, v238, v30, v31
	v_max3_f32 v238, v238, v32, v33
	v_max3_f32 v238, v238, v86, v87
	v_max3_f32 v238, v238, v88, v89
	v_xor_b32_e32 v242, 16, v195
	v_lshlrev_b32_e32 v242, 2, v242
	ds_bpermute_b32 v242, v242, v238
	s_waitcnt lgkmcnt(0)
	v_max_f32_e32 v238, v238, v242
	v_xor_b32_e32 v242, 32, v195
	v_lshlrev_b32_e32 v242, 2, v242
	ds_bpermute_b32 v242, v242, v238
	s_waitcnt lgkmcnt(0)
	v_max_f32_e32 v238, v238, v242
	v_mul_f32_e32 v238, 0x3e000000, v238
	v_max_f32_e32 v238, v238, v85
	v_mul_f32_e32 v243, 0xbfb8aa3b, v238
	v_fmamk_f32 v2, v2, 0x3e38aa3b, v243
	v_fmamk_f32 v3, v3, 0x3e38aa3b, v243
	v_fmamk_f32 v4, v4, 0x3e38aa3b, v243
	v_fmamk_f32 v5, v5, 0x3e38aa3b, v243
	v_exp_f32_e32 v2, v2
	v_exp_f32_e32 v3, v3
	v_exp_f32_e32 v4, v4
	v_exp_f32_e32 v5, v5
	v_fmamk_f32 v6, v6, 0x3e38aa3b, v243
	v_fmamk_f32 v7, v7, 0x3e38aa3b, v243
	v_fmamk_f32 v8, v8, 0x3e38aa3b, v243
	v_fmamk_f32 v9, v9, 0x3e38aa3b, v243
	v_exp_f32_e32 v6, v6
	v_exp_f32_e32 v7, v7
	v_exp_f32_e32 v8, v8
	v_exp_f32_e32 v9, v9
	v_add_f32_e32 v239, 0, v2
	v_add_f32_e32 v239, v239, v3
	v_add_f32_e32 v239, v239, v4
	v_add_f32_e32 v239, v239, v5
	v_fmamk_f32 v10, v10, 0x3e38aa3b, v243
	v_fmamk_f32 v11, v11, 0x3e38aa3b, v243
	v_fmamk_f32 v12, v12, 0x3e38aa3b, v243
	v_fmamk_f32 v13, v13, 0x3e38aa3b, v243
	v_exp_f32_e32 v10, v10
	v_exp_f32_e32 v11, v11
	v_exp_f32_e32 v12, v12
	v_exp_f32_e32 v13, v13
	v_add_f32_e32 v239, v239, v6
	v_add_f32_e32 v239, v239, v7
	v_add_f32_e32 v239, v239, v8
	v_add_f32_e32 v239, v239, v9
	v_fmamk_f32 v14, v14, 0x3e38aa3b, v243
	v_fmamk_f32 v15, v15, 0x3e38aa3b, v243
	v_fmamk_f32 v16, v16, 0x3e38aa3b, v243
	v_fmamk_f32 v17, v17, 0x3e38aa3b, v243
	v_exp_f32_e32 v14, v14
	v_exp_f32_e32 v15, v15
	v_exp_f32_e32 v16, v16
	v_exp_f32_e32 v17, v17
	v_add_f32_e32 v239, v239, v10
	v_add_f32_e32 v239, v239, v11
	v_add_f32_e32 v239, v239, v12
	v_add_f32_e32 v239, v239, v13
	v_fmamk_f32 v18, v18, 0x3e38aa3b, v243
	v_fmamk_f32 v19, v19, 0x3e38aa3b, v243
	v_fmamk_f32 v20, v20, 0x3e38aa3b, v243
	v_fmamk_f32 v21, v21, 0x3e38aa3b, v243
	v_exp_f32_e32 v18, v18
	v_exp_f32_e32 v19, v19
	v_exp_f32_e32 v20, v20
	v_exp_f32_e32 v21, v21
	v_add_f32_e32 v239, v239, v14
	v_add_f32_e32 v239, v239, v15
	v_add_f32_e32 v239, v239, v16
	v_add_f32_e32 v239, v239, v17
	v_fmamk_f32 v22, v22, 0x3e38aa3b, v243
	v_fmamk_f32 v23, v23, 0x3e38aa3b, v243
	v_fmamk_f32 v24, v24, 0x3e38aa3b, v243
	v_fmamk_f32 v25, v25, 0x3e38aa3b, v243
	v_exp_f32_e32 v22, v22
	v_exp_f32_e32 v23, v23
	v_exp_f32_e32 v24, v24
	v_exp_f32_e32 v25, v25
	v_add_f32_e32 v239, v239, v18
	v_add_f32_e32 v239, v239, v19
	v_add_f32_e32 v239, v239, v20
	v_add_f32_e32 v239, v239, v21
	v_fmamk_f32 v26, v26, 0x3e38aa3b, v243
	v_fmamk_f32 v27, v27, 0x3e38aa3b, v243
	v_fmamk_f32 v28, v28, 0x3e38aa3b, v243
	v_fmamk_f32 v29, v29, 0x3e38aa3b, v243
	v_exp_f32_e32 v26, v26
	v_exp_f32_e32 v27, v27
	v_exp_f32_e32 v28, v28
	v_exp_f32_e32 v29, v29
	v_add_f32_e32 v239, v239, v22
	v_add_f32_e32 v239, v239, v23
	v_add_f32_e32 v239, v239, v24
	v_add_f32_e32 v239, v239, v25
	v_fmamk_f32 v30, v30, 0x3e38aa3b, v243
	v_fmamk_f32 v31, v31, 0x3e38aa3b, v243
	v_fmamk_f32 v32, v32, 0x3e38aa3b, v243
	v_fmamk_f32 v33, v33, 0x3e38aa3b, v243
	v_exp_f32_e32 v30, v30
	v_exp_f32_e32 v31, v31
	v_exp_f32_e32 v32, v32
	v_exp_f32_e32 v33, v33
	v_add_f32_e32 v239, v239, v26
	v_add_f32_e32 v239, v239, v27
	v_add_f32_e32 v239, v239, v28
	v_add_f32_e32 v239, v239, v29
	v_fmamk_f32 v86, v86, 0x3e38aa3b, v243
	v_fmamk_f32 v87, v87, 0x3e38aa3b, v243
	v_fmamk_f32 v88, v88, 0x3e38aa3b, v243
	v_fmamk_f32 v89, v89, 0x3e38aa3b, v243
	v_exp_f32_e32 v86, v86
	v_exp_f32_e32 v87, v87
	v_exp_f32_e32 v88, v88
	v_exp_f32_e32 v89, v89
	v_add_f32_e32 v239, v239, v30
	v_add_f32_e32 v239, v239, v31
	v_add_f32_e32 v239, v239, v32
	v_add_f32_e32 v239, v239, v33
	s_nop 0
	v_add_f32_e32 v239, v239, v86
	v_add_f32_e32 v239, v239, v87
	v_add_f32_e32 v239, v239, v88
	v_add_f32_e32 v239, v239, v89
	v_xor_b32_e32 v242, 16, v195
	v_lshlrev_b32_e32 v242, 2, v242
	ds_bpermute_b32 v242, v242, v239
	s_waitcnt lgkmcnt(0)
	v_add_f32_e32 v239, v239, v242
	v_xor_b32_e32 v242, 32, v195
	v_lshlrev_b32_e32 v242, 2, v242
	ds_bpermute_b32 v242, v242, v239
	s_waitcnt lgkmcnt(0)
	v_add_f32_e32 v239, v239, v242
	v_sub_f32_e32 v242, v85, v238
	v_mul_f32_e32 v242, 0x3fb8aa3b, v242
	v_exp_f32_e32 v242, v242
	s_nop 0
	v_add_f32_e32 v239, v239, v242
	v_rcp_f32_e32 v244, v239
	v_cvt_pk_bf16_f32 v218, v2, v3
	v_cvt_pk_bf16_f32 v219, v4, v5
	v_cvt_pk_bf16_f32 v220, v6, v7
	v_cvt_pk_bf16_f32 v221, v8, v9
	v_cvt_pk_bf16_f32 v222, v10, v11
	v_cvt_pk_bf16_f32 v223, v12, v13
	v_cvt_pk_bf16_f32 v224, v14, v15
	v_cvt_pk_bf16_f32 v225, v16, v17
	v_cvt_pk_bf16_f32 v226, v18, v19
	v_cvt_pk_bf16_f32 v227, v20, v21
	v_cvt_pk_bf16_f32 v228, v22, v23
	v_cvt_pk_bf16_f32 v229, v24, v25
	v_cvt_pk_bf16_f32 v230, v26, v27
	v_cvt_pk_bf16_f32 v231, v28, v29
	v_cvt_pk_bf16_f32 v232, v30, v31
	v_cvt_pk_bf16_f32 v233, v32, v33
	v_cvt_pk_bf16_f32 v234, v86, v87
	v_cvt_pk_bf16_f32 v235, v88, v89
	v_mov_b32_e32 v236, 0
	v_mov_b32_e32 v237, 0
	ds_read_b64 v[182:183], v245
	ds_read_b64 v[184:185], v245 offset:32
	ds_read_b64 v[186:187], v245 offset:8448
	ds_read_b64 v[188:189], v245 offset:8480
	ds_read_b64 v[190:191], v245 offset:16896
	ds_read_b64 v[192:193], v245 offset:16928
	ds_read_b64 v[210:211], v245 offset:25344
	ds_read_b64 v[212:213], v245 offset:25376
	ds_read_b64 v[214:215], v245 offset:64
	ds_read_b64 v[216:217], v245 offset:96
	s_waitcnt lgkmcnt(8)
	v_mfma_f32_16x16x32_bf16 v[142:145], v[182:185], v[218:221], 0
	ds_read_b64 v[182:183], v245 offset:8512
	ds_read_b64 v[184:185], v245 offset:8544
	s_waitcnt lgkmcnt(8)
	v_mfma_f32_16x16x32_bf16 v[146:149], v[186:189], v[218:221], 0
	ds_read_b64 v[186:187], v245 offset:16960
	ds_read_b64 v[188:189], v245 offset:16992
	s_waitcnt lgkmcnt(8)
	v_mfma_f32_16x16x32_bf16 v[150:153], v[190:193], v[218:221], 0
	ds_read_b64 v[190:191], v245 offset:25408
	ds_read_b64 v[192:193], v245 offset:25440
	s_waitcnt lgkmcnt(8)
	v_mfma_f32_16x16x32_bf16 v[154:157], v[210:213], v[218:221], 0
	ds_read_b64 v[210:211], v245 offset:128
	ds_read_b64 v[212:213], v245 offset:160
	s_waitcnt lgkmcnt(8)
	v_mfma_f32_16x16x32_bf16 v[142:145], v[214:217], v[222:225], v[142:145]
	ds_read_b64 v[214:215], v245 offset:8576
	ds_read_b64 v[216:217], v245 offset:8608
	s_waitcnt lgkmcnt(8)
	v_mfma_f32_16x16x32_bf16 v[146:149], v[182:185], v[222:225], v[146:149]
	ds_read_b64 v[182:183], v245 offset:17024
	ds_read_b64 v[184:185], v245 offset:17056
	s_waitcnt lgkmcnt(8)
	v_mfma_f32_16x16x32_bf16 v[150:153], v[186:189], v[222:225], v[150:153]
	ds_read_b64 v[186:187], v245 offset:25472
	ds_read_b64 v[188:189], v245 offset:25504
	s_waitcnt lgkmcnt(8)
	v_mfma_f32_16x16x32_bf16 v[154:157], v[190:193], v[222:225], v[154:157]
	ds_read_b64 v[190:191], v245 offset:192
	ds_read_b64 v[192:193], v245 offset:224
	s_waitcnt lgkmcnt(8)
	v_mfma_f32_16x16x32_bf16 v[142:145], v[210:213], v[226:229], v[142:145]
	ds_read_b64 v[210:211], v245 offset:8640
	ds_read_b64 v[212:213], v245 offset:8672
	s_waitcnt lgkmcnt(8)
	v_mfma_f32_16x16x32_bf16 v[146:149], v[214:217], v[226:229], v[146:149]
	ds_read_b64 v[214:215], v245 offset:17088
	ds_read_b64 v[216:217], v245 offset:17120
	s_waitcnt lgkmcnt(8)
	v_mfma_f32_16x16x32_bf16 v[150:153], v[182:185], v[226:229], v[150:153]
	ds_read_b64 v[182:183], v245 offset:25536
	ds_read_b64 v[184:185], v245 offset:25568
	s_waitcnt lgkmcnt(8)
	v_mfma_f32_16x16x32_bf16 v[154:157], v[186:189], v[226:229], v[154:157]
	ds_read_b64 v[186:187], v245 offset:256
	ds_read_b64 v[188:189], v245 offset:256
	s_waitcnt lgkmcnt(8)
	v_mfma_f32_16x16x32_bf16 v[142:145], v[190:193], v[230:233], v[142:145]
	ds_read_b64 v[190:191], v245 offset:8704
	ds_read_b64 v[192:193], v245 offset:8704
	s_waitcnt lgkmcnt(8)
	v_mfma_f32_16x16x32_bf16 v[146:149], v[210:213], v[230:233], v[146:149]
	ds_read_b64 v[210:211], v245 offset:17152
	ds_read_b64 v[212:213], v245 offset:17152
	s_waitcnt lgkmcnt(8)
	v_mfma_f32_16x16x32_bf16 v[150:153], v[214:217], v[230:233], v[150:153]
	ds_read_b64 v[214:215], v245 offset:25600
	ds_read_b64 v[216:217], v245 offset:25600
	s_waitcnt lgkmcnt(8)
	v_mfma_f32_16x16x32_bf16 v[154:157], v[182:185], v[230:233], v[154:157]
	s_waitcnt lgkmcnt(6)
	v_mfma_f32_16x16x32_bf16 v[142:145], v[186:189], v[234:237], v[142:145]
	s_waitcnt lgkmcnt(4)
	v_mfma_f32_16x16x32_bf16 v[146:149], v[190:193], v[234:237], v[146:149]
	s_waitcnt lgkmcnt(2)
	v_mfma_f32_16x16x32_bf16 v[150:153], v[210:213], v[234:237], v[150:153]
	s_waitcnt lgkmcnt(0)
	v_mfma_f32_16x16x32_bf16 v[154:157], v[214:217], v[234:237], v[154:157]
	s_nop 7
	s_nop 1
	v_mul_f32_e32 v142, v244, v142
	v_mul_f32_e32 v143, v244, v143
	v_mul_f32_e32 v144, v244, v144
	v_mul_f32_e32 v145, v244, v145
	v_mul_f32_e32 v146, v244, v146
	v_mul_f32_e32 v147, v244, v147
	v_mul_f32_e32 v148, v244, v148
	v_mul_f32_e32 v149, v244, v149
	v_cvt_pk_bf16_f32 v240, v142, v143
	v_cvt_pk_bf16_f32 v241, v144, v145
	v_cvt_pk_bf16_f32 v242, v146, v147
	v_cvt_pk_bf16_f32 v243, v148, v149
	global_store_dwordx4 v[246:247], v[240:243], off
	s_nop 1
	v_mul_f32_e32 v150, v244, v150
	v_mul_f32_e32 v151, v244, v151
	v_mul_f32_e32 v152, v244, v152
	v_mul_f32_e32 v153, v244, v153
	v_mul_f32_e32 v154, v244, v154
	v_mul_f32_e32 v155, v244, v155
	v_mul_f32_e32 v156, v244, v156
	v_mul_f32_e32 v157, v244, v157
	v_cvt_pk_bf16_f32 v240, v150, v151
	v_cvt_pk_bf16_f32 v241, v152, v153
	v_cvt_pk_bf16_f32 v242, v154, v155
	v_cvt_pk_bf16_f32 v243, v156, v157
	global_store_dwordx4 v[246:247], v[240:243], off offset:64
	v_lshl_add_u64 v[246:247], v[246:247], 0, s[8:9]
	s_waitcnt vmcnt(2)
	ds_read_b128 v[106:109], v118 offset:2304
	ds_read_b128 v[110:113], v118 offset:2368
	ds_read_b128 v[114:117], v118 offset:4608
	ds_read_b128 v[128:131], v118 offset:4672
	ds_read_b128 v[132:135], v118 offset:6912
	ds_read_b128 v[120:123], v118 offset:6976
	s_waitcnt lgkmcnt(5)
	v_mfma_f32_16x16x32_bf16 v[2:5], v[106:109], v[98:101], 0
	ds_read_b128 v[106:109], v118 offset:9216
	s_waitcnt lgkmcnt(5)
	v_mfma_f32_16x16x32_bf16 v[2:5], v[110:113], v[102:105], v[2:5]
	ds_read_b128 v[110:113], v118 offset:9280
	s_waitcnt lgkmcnt(5)
	v_mfma_f32_16x16x32_bf16 v[6:9], v[114:117], v[98:101], 0
	ds_read_b128 v[114:117], v118 offset:11520
	s_waitcnt lgkmcnt(5)
	v_mfma_f32_16x16x32_bf16 v[6:9], v[128:131], v[102:105], v[6:9]
	ds_read_b128 v[128:131], v118 offset:11584
	s_waitcnt lgkmcnt(5)
	v_mfma_f32_16x16x32_bf16 v[10:13], v[132:135], v[98:101], 0
	ds_read_b128 v[132:135], v118 offset:13824
	s_waitcnt lgkmcnt(5)
	v_mfma_f32_16x16x32_bf16 v[10:13], v[120:123], v[102:105], v[10:13]
	ds_read_b128 v[120:123], v118 offset:13888
	s_waitcnt lgkmcnt(5)
	v_mfma_f32_16x16x32_bf16 v[14:17], v[106:109], v[98:101], 0
	ds_read_b128 v[106:109], v118 offset:16128
	s_waitcnt lgkmcnt(5)
	v_mfma_f32_16x16x32_bf16 v[14:17], v[110:113], v[102:105], v[14:17]
	ds_read_b128 v[110:113], v118 offset:16192
	s_waitcnt lgkmcnt(5)
	v_mfma_f32_16x16x32_bf16 v[18:21], v[114:117], v[98:101], 0
	ds_read_b128 v[114:117], v118 offset:18432
	s_waitcnt lgkmcnt(5)
	v_mfma_f32_16x16x32_bf16 v[18:21], v[128:131], v[102:105], v[18:21]
	ds_read_b128 v[128:131], v118 offset:18496
	s_waitcnt lgkmcnt(5)
	v_mfma_f32_16x16x32_bf16 v[22:25], v[132:135], v[98:101], 0
	ds_read_b128 v[132:135], v118 offset:20736
	s_waitcnt lgkmcnt(5)
	v_mfma_f32_16x16x32_bf16 v[22:25], v[120:123], v[102:105], v[22:25]
	ds_read_b128 v[120:123], v118 offset:20800
	s_waitcnt lgkmcnt(5)
	v_mfma_f32_16x16x32_bf16 v[26:29], v[106:109], v[98:101], 0
	s_waitcnt lgkmcnt(4)
	v_mfma_f32_16x16x32_bf16 v[26:29], v[110:113], v[102:105], v[26:29]
	s_waitcnt lgkmcnt(3)
	v_mfma_f32_16x16x32_bf16 v[30:33], v[114:117], v[98:101], 0
	s_waitcnt lgkmcnt(2)
	v_mfma_f32_16x16x32_bf16 v[30:33], v[128:131], v[102:105], v[30:33]
	s_waitcnt lgkmcnt(1)
	v_mfma_f32_16x16x32_bf16 v[86:89], v[132:135], v[98:101], 0
	s_waitcnt lgkmcnt(0)
	v_mfma_f32_16x16x32_bf16 v[86:89], v[120:123], v[102:105], v[86:89]
	v_lshl_add_u64 v[240:241], v[246:247], 0, s[8:9]
	global_load_dwordx4 v[90:93], v[240:241], off
	global_load_dwordx4 v[94:97], v[240:241], off offset:64
	v_add_u32_e32 v242, 0, v249
	v_cmp_gt_u32_e32 vcc, v242, v248
	s_nop 1
	s_and_b64 vcc, vcc, s[66:67]
	s_nop 0
	v_cndmask_b32_e32 v2, v205, v2, vcc
	v_add_u32_e32 v242, 1, v249
	v_cmp_gt_u32_e32 vcc, v242, v248
	s_nop 1
	s_and_b64 vcc, vcc, s[66:67]
	s_nop 0
	v_cndmask_b32_e32 v3, v205, v3, vcc
	v_add_u32_e32 v242, 2, v249
	v_cmp_gt_u32_e32 vcc, v242, v248
	s_nop 1
	s_and_b64 vcc, vcc, s[66:67]
	s_nop 0
	v_cndmask_b32_e32 v4, v205, v4, vcc
	v_add_u32_e32 v242, 3, v249
	v_cmp_gt_u32_e32 vcc, v242, v248
	s_nop 1
	s_and_b64 vcc, vcc, s[66:67]
	s_nop 0
	v_cndmask_b32_e32 v5, v205, v5, vcc
	v_cndmask_b32_e64 v6, v205, v6, s[66:67]
	v_cndmask_b32_e64 v7, v205, v7, s[66:67]
	v_cndmask_b32_e64 v8, v205, v8, s[66:67]
	v_cndmask_b32_e64 v9, v205, v9, s[66:67]
	v_cndmask_b32_e64 v10, v205, v10, s[66:67]
	v_cndmask_b32_e64 v11, v205, v11, s[66:67]
	v_cndmask_b32_e64 v12, v205, v12, s[66:67]
	v_cndmask_b32_e64 v13, v205, v13, s[66:67]
	v_cndmask_b32_e64 v14, v205, v14, s[66:67]
	v_cndmask_b32_e64 v15, v205, v15, s[66:67]
	v_cndmask_b32_e64 v16, v205, v16, s[66:67]
	v_cndmask_b32_e64 v17, v205, v17, s[66:67]
	v_cndmask_b32_e64 v18, v205, v18, s[66:67]
	v_cndmask_b32_e64 v19, v205, v19, s[66:67]
	v_cndmask_b32_e64 v20, v205, v20, s[66:67]
	v_cndmask_b32_e64 v21, v205, v21, s[66:67]
	v_cndmask_b32_e64 v22, v205, v22, s[66:67]
	v_cndmask_b32_e64 v23, v205, v23, s[66:67]
	v_cndmask_b32_e64 v24, v205, v24, s[66:67]
	v_cndmask_b32_e64 v25, v205, v25, s[66:67]
	v_cndmask_b32_e64 v26, v205, v26, s[66:67]
	v_cndmask_b32_e64 v27, v205, v27, s[66:67]
	v_cndmask_b32_e64 v28, v205, v28, s[66:67]
	v_cndmask_b32_e64 v29, v205, v29, s[66:67]
	v_add_u32_e32 v242, 0, v249
	v_cmp_le_u32_e32 vcc, v242, v248
	s_nop 1
	v_cndmask_b32_e32 v86, v205, v86, vcc
	v_add_u32_e32 v242, 1, v249
	v_cmp_le_u32_e32 vcc, v242, v248
	s_nop 1
	v_cndmask_b32_e32 v87, v205, v87, vcc
	v_add_u32_e32 v242, 2, v249
	v_cmp_le_u32_e32 vcc, v242, v248
	s_nop 1
	v_cndmask_b32_e32 v88, v205, v88, vcc
	v_add_u32_e32 v242, 3, v249
	v_cmp_le_u32_e32 vcc, v242, v248
	s_nop 1
	v_cndmask_b32_e32 v89, v205, v89, vcc
	v_max3_f32 v238, v2, v3, v205
	v_max3_f32 v238, v238, v4, v5
	v_max3_f32 v238, v238, v6, v7
	v_max3_f32 v238, v238, v8, v9
	v_max3_f32 v238, v238, v10, v11
	v_max3_f32 v238, v238, v12, v13
	v_max3_f32 v238, v238, v14, v15
	v_max3_f32 v238, v238, v16, v17
	v_max3_f32 v238, v238, v18, v19
	v_max3_f32 v238, v238, v20, v21
	v_max3_f32 v238, v238, v22, v23
	v_max3_f32 v238, v238, v24, v25
	v_max3_f32 v238, v238, v26, v27
	v_max3_f32 v238, v238, v28, v29
	v_max3_f32 v238, v238, v30, v31
	v_max3_f32 v238, v238, v32, v33
	v_max3_f32 v238, v238, v86, v87
	v_max3_f32 v238, v238, v88, v89
	v_xor_b32_e32 v242, 16, v195
	v_lshlrev_b32_e32 v242, 2, v242
	ds_bpermute_b32 v242, v242, v238
	s_waitcnt lgkmcnt(0)
	v_max_f32_e32 v238, v238, v242
	v_xor_b32_e32 v242, 32, v195
	v_lshlrev_b32_e32 v242, 2, v242
	ds_bpermute_b32 v242, v242, v238
	s_waitcnt lgkmcnt(0)
	v_max_f32_e32 v238, v238, v242
	v_mul_f32_e32 v238, 0x3e000000, v238
	v_max_f32_e32 v238, v238, v85
	v_mul_f32_e32 v243, 0xbfb8aa3b, v238
	v_fmamk_f32 v2, v2, 0x3e38aa3b, v243
	v_fmamk_f32 v3, v3, 0x3e38aa3b, v243
	v_fmamk_f32 v4, v4, 0x3e38aa3b, v243
	v_fmamk_f32 v5, v5, 0x3e38aa3b, v243
	v_exp_f32_e32 v2, v2
	v_exp_f32_e32 v3, v3
	v_exp_f32_e32 v4, v4
	v_exp_f32_e32 v5, v5
	v_fmamk_f32 v6, v6, 0x3e38aa3b, v243
	v_fmamk_f32 v7, v7, 0x3e38aa3b, v243
	v_fmamk_f32 v8, v8, 0x3e38aa3b, v243
	v_fmamk_f32 v9, v9, 0x3e38aa3b, v243
	v_exp_f32_e32 v6, v6
	v_exp_f32_e32 v7, v7
	v_exp_f32_e32 v8, v8
	v_exp_f32_e32 v9, v9
	v_add_f32_e32 v239, 0, v2
	v_add_f32_e32 v239, v239, v3
	v_add_f32_e32 v239, v239, v4
	v_add_f32_e32 v239, v239, v5
	v_fmamk_f32 v10, v10, 0x3e38aa3b, v243
	v_fmamk_f32 v11, v11, 0x3e38aa3b, v243
	v_fmamk_f32 v12, v12, 0x3e38aa3b, v243
	v_fmamk_f32 v13, v13, 0x3e38aa3b, v243
	v_exp_f32_e32 v10, v10
	v_exp_f32_e32 v11, v11
	v_exp_f32_e32 v12, v12
	v_exp_f32_e32 v13, v13
	v_add_f32_e32 v239, v239, v6
	v_add_f32_e32 v239, v239, v7
	v_add_f32_e32 v239, v239, v8
	v_add_f32_e32 v239, v239, v9
	v_fmamk_f32 v14, v14, 0x3e38aa3b, v243
	v_fmamk_f32 v15, v15, 0x3e38aa3b, v243
	v_fmamk_f32 v16, v16, 0x3e38aa3b, v243
	v_fmamk_f32 v17, v17, 0x3e38aa3b, v243
	v_exp_f32_e32 v14, v14
	v_exp_f32_e32 v15, v15
	v_exp_f32_e32 v16, v16
	v_exp_f32_e32 v17, v17
	v_add_f32_e32 v239, v239, v10
	v_add_f32_e32 v239, v239, v11
	v_add_f32_e32 v239, v239, v12
	v_add_f32_e32 v239, v239, v13
	v_fmamk_f32 v18, v18, 0x3e38aa3b, v243
	v_fmamk_f32 v19, v19, 0x3e38aa3b, v243
	v_fmamk_f32 v20, v20, 0x3e38aa3b, v243
	v_fmamk_f32 v21, v21, 0x3e38aa3b, v243
	v_exp_f32_e32 v18, v18
	v_exp_f32_e32 v19, v19
	v_exp_f32_e32 v20, v20
	v_exp_f32_e32 v21, v21
	v_add_f32_e32 v239, v239, v14
	v_add_f32_e32 v239, v239, v15
	v_add_f32_e32 v239, v239, v16
	v_add_f32_e32 v239, v239, v17
	v_fmamk_f32 v22, v22, 0x3e38aa3b, v243
	v_fmamk_f32 v23, v23, 0x3e38aa3b, v243
	v_fmamk_f32 v24, v24, 0x3e38aa3b, v243
	v_fmamk_f32 v25, v25, 0x3e38aa3b, v243
	v_exp_f32_e32 v22, v22
	v_exp_f32_e32 v23, v23
	v_exp_f32_e32 v24, v24
	v_exp_f32_e32 v25, v25
	v_add_f32_e32 v239, v239, v18
	v_add_f32_e32 v239, v239, v19
	v_add_f32_e32 v239, v239, v20
	v_add_f32_e32 v239, v239, v21
	v_fmamk_f32 v26, v26, 0x3e38aa3b, v243
	v_fmamk_f32 v27, v27, 0x3e38aa3b, v243
	v_fmamk_f32 v28, v28, 0x3e38aa3b, v243
	v_fmamk_f32 v29, v29, 0x3e38aa3b, v243
	v_exp_f32_e32 v26, v26
	v_exp_f32_e32 v27, v27
	v_exp_f32_e32 v28, v28
	v_exp_f32_e32 v29, v29
	v_add_f32_e32 v239, v239, v22
	v_add_f32_e32 v239, v239, v23
	v_add_f32_e32 v239, v239, v24
	v_add_f32_e32 v239, v239, v25
	v_fmamk_f32 v30, v30, 0x3e38aa3b, v243
	v_fmamk_f32 v31, v31, 0x3e38aa3b, v243
	v_fmamk_f32 v32, v32, 0x3e38aa3b, v243
	v_fmamk_f32 v33, v33, 0x3e38aa3b, v243
	v_exp_f32_e32 v30, v30
	v_exp_f32_e32 v31, v31
	v_exp_f32_e32 v32, v32
	v_exp_f32_e32 v33, v33
	v_add_f32_e32 v239, v239, v26
	v_add_f32_e32 v239, v239, v27
	v_add_f32_e32 v239, v239, v28
	v_add_f32_e32 v239, v239, v29
	v_fmamk_f32 v86, v86, 0x3e38aa3b, v243
	v_fmamk_f32 v87, v87, 0x3e38aa3b, v243
	v_fmamk_f32 v88, v88, 0x3e38aa3b, v243
	v_fmamk_f32 v89, v89, 0x3e38aa3b, v243
	v_exp_f32_e32 v86, v86
	v_exp_f32_e32 v87, v87
	v_exp_f32_e32 v88, v88
	v_exp_f32_e32 v89, v89
	v_add_f32_e32 v239, v239, v30
	v_add_f32_e32 v239, v239, v31
	v_add_f32_e32 v239, v239, v32
	v_add_f32_e32 v239, v239, v33
	s_nop 0
	v_add_f32_e32 v239, v239, v86
	v_add_f32_e32 v239, v239, v87
	v_add_f32_e32 v239, v239, v88
	v_add_f32_e32 v239, v239, v89
	v_xor_b32_e32 v242, 16, v195
	v_lshlrev_b32_e32 v242, 2, v242
	ds_bpermute_b32 v242, v242, v239
	s_waitcnt lgkmcnt(0)
	v_add_f32_e32 v239, v239, v242
	v_xor_b32_e32 v242, 32, v195
	v_lshlrev_b32_e32 v242, 2, v242
	ds_bpermute_b32 v242, v242, v239
	s_waitcnt lgkmcnt(0)
	v_add_f32_e32 v239, v239, v242
	v_sub_f32_e32 v242, v85, v238
	v_mul_f32_e32 v242, 0x3fb8aa3b, v242
	v_exp_f32_e32 v242, v242
	s_nop 0
	v_add_f32_e32 v239, v239, v242
	v_rcp_f32_e32 v244, v239
	v_cvt_pk_bf16_f32 v218, v2, v3
	v_cvt_pk_bf16_f32 v219, v4, v5
	v_cvt_pk_bf16_f32 v220, v6, v7
	v_cvt_pk_bf16_f32 v221, v8, v9
	v_cvt_pk_bf16_f32 v222, v10, v11
	v_cvt_pk_bf16_f32 v223, v12, v13
	v_cvt_pk_bf16_f32 v224, v14, v15
	v_cvt_pk_bf16_f32 v225, v16, v17
	v_cvt_pk_bf16_f32 v226, v18, v19
	v_cvt_pk_bf16_f32 v227, v20, v21
	v_cvt_pk_bf16_f32 v228, v22, v23
	v_cvt_pk_bf16_f32 v229, v24, v25
	v_cvt_pk_bf16_f32 v230, v26, v27
	v_cvt_pk_bf16_f32 v231, v28, v29
	v_cvt_pk_bf16_f32 v232, v30, v31
	v_cvt_pk_bf16_f32 v233, v32, v33
	v_cvt_pk_bf16_f32 v234, v86, v87
	v_cvt_pk_bf16_f32 v235, v88, v89
	v_mov_b32_e32 v236, 0
	v_mov_b32_e32 v237, 0
	ds_read_b64 v[182:183], v245 offset:32
	ds_read_b64 v[184:185], v245 offset:64
	ds_read_b64 v[186:187], v245 offset:8480
	ds_read_b64 v[188:189], v245 offset:8512
	ds_read_b64 v[190:191], v245 offset:16928
	ds_read_b64 v[192:193], v245 offset:16960
	ds_read_b64 v[210:211], v245 offset:25376
	ds_read_b64 v[212:213], v245 offset:25408
	ds_read_b64 v[214:215], v245 offset:96
	ds_read_b64 v[216:217], v245 offset:128
	s_waitcnt lgkmcnt(8)
	v_mfma_f32_16x16x32_bf16 v[142:145], v[182:185], v[218:221], 0
	ds_read_b64 v[182:183], v245 offset:8544
	ds_read_b64 v[184:185], v245 offset:8576
	s_waitcnt lgkmcnt(8)
	v_mfma_f32_16x16x32_bf16 v[146:149], v[186:189], v[218:221], 0
	ds_read_b64 v[186:187], v245 offset:16992
	ds_read_b64 v[188:189], v245 offset:17024
	s_waitcnt lgkmcnt(8)
	v_mfma_f32_16x16x32_bf16 v[150:153], v[190:193], v[218:221], 0
	ds_read_b64 v[190:191], v245 offset:25440
	ds_read_b64 v[192:193], v245 offset:25472
	s_waitcnt lgkmcnt(8)
	v_mfma_f32_16x16x32_bf16 v[154:157], v[210:213], v[218:221], 0
	ds_read_b64 v[210:211], v245 offset:160
	ds_read_b64 v[212:213], v245 offset:192
	s_waitcnt lgkmcnt(8)
	v_mfma_f32_16x16x32_bf16 v[142:145], v[214:217], v[222:225], v[142:145]
	ds_read_b64 v[214:215], v245 offset:8608
	ds_read_b64 v[216:217], v245 offset:8640
	s_waitcnt lgkmcnt(8)
	v_mfma_f32_16x16x32_bf16 v[146:149], v[182:185], v[222:225], v[146:149]
	ds_read_b64 v[182:183], v245 offset:17056
	ds_read_b64 v[184:185], v245 offset:17088
	s_waitcnt lgkmcnt(8)
	v_mfma_f32_16x16x32_bf16 v[150:153], v[186:189], v[222:225], v[150:153]
	ds_read_b64 v[186:187], v245 offset:25504
	ds_read_b64 v[188:189], v245 offset:25536
	s_waitcnt lgkmcnt(8)
	v_mfma_f32_16x16x32_bf16 v[154:157], v[190:193], v[222:225], v[154:157]
	ds_read_b64 v[190:191], v245 offset:224
	ds_read_b64 v[192:193], v245 offset:256
	s_waitcnt lgkmcnt(8)
	v_mfma_f32_16x16x32_bf16 v[142:145], v[210:213], v[226:229], v[142:145]
	ds_read_b64 v[210:211], v245 offset:8672
	ds_read_b64 v[212:213], v245 offset:8704
	s_waitcnt lgkmcnt(8)
	v_mfma_f32_16x16x32_bf16 v[146:149], v[214:217], v[226:229], v[146:149]
	ds_read_b64 v[214:215], v245 offset:17120
	ds_read_b64 v[216:217], v245 offset:17152
	s_waitcnt lgkmcnt(8)
	v_mfma_f32_16x16x32_bf16 v[150:153], v[182:185], v[226:229], v[150:153]
	ds_read_b64 v[182:183], v245 offset:25568
	ds_read_b64 v[184:185], v245 offset:25600
	s_waitcnt lgkmcnt(8)
	v_mfma_f32_16x16x32_bf16 v[154:157], v[186:189], v[226:229], v[154:157]
	ds_read_b64 v[186:187], v245 offset:288
	ds_read_b64 v[188:189], v245 offset:288
	s_waitcnt lgkmcnt(8)
	v_mfma_f32_16x16x32_bf16 v[142:145], v[190:193], v[230:233], v[142:145]
	ds_read_b64 v[190:191], v245 offset:8736
	ds_read_b64 v[192:193], v245 offset:8736
	s_waitcnt lgkmcnt(8)
	v_mfma_f32_16x16x32_bf16 v[146:149], v[210:213], v[230:233], v[146:149]
	ds_read_b64 v[210:211], v245 offset:17184
	ds_read_b64 v[212:213], v245 offset:17184
	s_waitcnt lgkmcnt(8)
	v_mfma_f32_16x16x32_bf16 v[150:153], v[214:217], v[230:233], v[150:153]
	ds_read_b64 v[214:215], v245 offset:25632
	ds_read_b64 v[216:217], v245 offset:25632
	s_waitcnt lgkmcnt(8)
	v_mfma_f32_16x16x32_bf16 v[154:157], v[182:185], v[230:233], v[154:157]
	s_waitcnt lgkmcnt(6)
	v_mfma_f32_16x16x32_bf16 v[142:145], v[186:189], v[234:237], v[142:145]
	s_waitcnt lgkmcnt(4)
	v_mfma_f32_16x16x32_bf16 v[146:149], v[190:193], v[234:237], v[146:149]
	s_waitcnt lgkmcnt(2)
	v_mfma_f32_16x16x32_bf16 v[150:153], v[210:213], v[234:237], v[150:153]
	s_waitcnt lgkmcnt(0)
	v_mfma_f32_16x16x32_bf16 v[154:157], v[214:217], v[234:237], v[154:157]
	s_nop 7
	s_nop 1
	v_mul_f32_e32 v142, v244, v142
	v_mul_f32_e32 v143, v244, v143
	v_mul_f32_e32 v144, v244, v144
	v_mul_f32_e32 v145, v244, v145
	v_mul_f32_e32 v146, v244, v146
	v_mul_f32_e32 v147, v244, v147
	v_mul_f32_e32 v148, v244, v148
	v_mul_f32_e32 v149, v244, v149
	v_cvt_pk_bf16_f32 v240, v142, v143
	v_cvt_pk_bf16_f32 v241, v144, v145
	v_cvt_pk_bf16_f32 v242, v146, v147
	v_cvt_pk_bf16_f32 v243, v148, v149
	global_store_dwordx4 v[246:247], v[240:243], off
	s_nop 1
	v_mul_f32_e32 v150, v244, v150
	v_mul_f32_e32 v151, v244, v151
	v_mul_f32_e32 v152, v244, v152
	v_mul_f32_e32 v153, v244, v153
	v_mul_f32_e32 v154, v244, v154
	v_mul_f32_e32 v155, v244, v155
	v_mul_f32_e32 v156, v244, v156
	v_mul_f32_e32 v157, v244, v157
	v_cvt_pk_bf16_f32 v240, v150, v151
	v_cvt_pk_bf16_f32 v241, v152, v153
	v_cvt_pk_bf16_f32 v242, v154, v155
	v_cvt_pk_bf16_f32 v243, v156, v157
	global_store_dwordx4 v[246:247], v[240:243], off offset:64
	v_lshl_add_u64 v[246:247], v[246:247], 0, s[8:9]
	s_waitcnt vmcnt(2)
	ds_read_b128 v[106:109], v118 offset:4608
	ds_read_b128 v[110:113], v118 offset:4672
	ds_read_b128 v[114:117], v118 offset:6912
	ds_read_b128 v[128:131], v118 offset:6976
	ds_read_b128 v[132:135], v118 offset:9216
	ds_read_b128 v[120:123], v118 offset:9280
	s_waitcnt lgkmcnt(5)
	v_mfma_f32_16x16x32_bf16 v[2:5], v[106:109], v[90:93], 0
	ds_read_b128 v[106:109], v118 offset:11520
	s_waitcnt lgkmcnt(5)
	v_mfma_f32_16x16x32_bf16 v[2:5], v[110:113], v[94:97], v[2:5]
	ds_read_b128 v[110:113], v118 offset:11584
	s_waitcnt lgkmcnt(5)
	v_mfma_f32_16x16x32_bf16 v[6:9], v[114:117], v[90:93], 0
	ds_read_b128 v[114:117], v118 offset:13824
	s_waitcnt lgkmcnt(5)
	v_mfma_f32_16x16x32_bf16 v[6:9], v[128:131], v[94:97], v[6:9]
	ds_read_b128 v[128:131], v118 offset:13888
	s_waitcnt lgkmcnt(5)
	v_mfma_f32_16x16x32_bf16 v[10:13], v[132:135], v[90:93], 0
	ds_read_b128 v[132:135], v118 offset:16128
	s_waitcnt lgkmcnt(5)
	v_mfma_f32_16x16x32_bf16 v[10:13], v[120:123], v[94:97], v[10:13]
	ds_read_b128 v[120:123], v118 offset:16192
	s_waitcnt lgkmcnt(5)
	v_mfma_f32_16x16x32_bf16 v[14:17], v[106:109], v[90:93], 0
	ds_read_b128 v[106:109], v118 offset:18432
	s_waitcnt lgkmcnt(5)
	v_mfma_f32_16x16x32_bf16 v[14:17], v[110:113], v[94:97], v[14:17]
	ds_read_b128 v[110:113], v118 offset:18496
	s_waitcnt lgkmcnt(5)
	v_mfma_f32_16x16x32_bf16 v[18:21], v[114:117], v[90:93], 0
	ds_read_b128 v[114:117], v118 offset:20736
	s_waitcnt lgkmcnt(5)
	v_mfma_f32_16x16x32_bf16 v[18:21], v[128:131], v[94:97], v[18:21]
	ds_read_b128 v[128:131], v118 offset:20800
	s_waitcnt lgkmcnt(5)
	v_mfma_f32_16x16x32_bf16 v[22:25], v[132:135], v[90:93], 0
	ds_read_b128 v[132:135], v118 offset:23040
	s_waitcnt lgkmcnt(5)
	v_mfma_f32_16x16x32_bf16 v[22:25], v[120:123], v[94:97], v[22:25]
	ds_read_b128 v[120:123], v118 offset:23104
	s_waitcnt lgkmcnt(5)
	v_mfma_f32_16x16x32_bf16 v[26:29], v[106:109], v[90:93], 0
	s_waitcnt lgkmcnt(4)
	v_mfma_f32_16x16x32_bf16 v[26:29], v[110:113], v[94:97], v[26:29]
	s_waitcnt lgkmcnt(3)
	v_mfma_f32_16x16x32_bf16 v[30:33], v[114:117], v[90:93], 0
	s_waitcnt lgkmcnt(2)
	v_mfma_f32_16x16x32_bf16 v[30:33], v[128:131], v[94:97], v[30:33]
	s_waitcnt lgkmcnt(1)
	v_mfma_f32_16x16x32_bf16 v[86:89], v[132:135], v[90:93], 0
	s_waitcnt lgkmcnt(0)
	v_mfma_f32_16x16x32_bf16 v[86:89], v[120:123], v[94:97], v[86:89]
	v_lshl_add_u64 v[240:241], v[246:247], 0, s[8:9]
	global_load_dwordx4 v[98:101], v[240:241], off
	global_load_dwordx4 v[102:105], v[240:241], off offset:64
	v_add_u32_e32 v242, 0, v249
	v_cmp_gt_u32_e32 vcc, v242, v248
	s_nop 1
	s_and_b64 vcc, vcc, s[66:67]
	s_nop 0
	v_cndmask_b32_e32 v2, v205, v2, vcc
	v_add_u32_e32 v242, 1, v249
	v_cmp_gt_u32_e32 vcc, v242, v248
	s_nop 1
	s_and_b64 vcc, vcc, s[66:67]
	s_nop 0
	v_cndmask_b32_e32 v3, v205, v3, vcc
	v_add_u32_e32 v242, 2, v249
	v_cmp_gt_u32_e32 vcc, v242, v248
	s_nop 1
	s_and_b64 vcc, vcc, s[66:67]
	s_nop 0
	v_cndmask_b32_e32 v4, v205, v4, vcc
	v_add_u32_e32 v242, 3, v249
	v_cmp_gt_u32_e32 vcc, v242, v248
	s_nop 1
	s_and_b64 vcc, vcc, s[66:67]
	s_nop 0
	v_cndmask_b32_e32 v5, v205, v5, vcc
	v_cndmask_b32_e64 v6, v205, v6, s[66:67]
	v_cndmask_b32_e64 v7, v205, v7, s[66:67]
	v_cndmask_b32_e64 v8, v205, v8, s[66:67]
	v_cndmask_b32_e64 v9, v205, v9, s[66:67]
	v_cndmask_b32_e64 v10, v205, v10, s[66:67]
	v_cndmask_b32_e64 v11, v205, v11, s[66:67]
	v_cndmask_b32_e64 v12, v205, v12, s[66:67]
	v_cndmask_b32_e64 v13, v205, v13, s[66:67]
	v_cndmask_b32_e64 v14, v205, v14, s[66:67]
	v_cndmask_b32_e64 v15, v205, v15, s[66:67]
	v_cndmask_b32_e64 v16, v205, v16, s[66:67]
	v_cndmask_b32_e64 v17, v205, v17, s[66:67]
	v_cndmask_b32_e64 v18, v205, v18, s[66:67]
	v_cndmask_b32_e64 v19, v205, v19, s[66:67]
	v_cndmask_b32_e64 v20, v205, v20, s[66:67]
	v_cndmask_b32_e64 v21, v205, v21, s[66:67]
	v_cndmask_b32_e64 v22, v205, v22, s[66:67]
	v_cndmask_b32_e64 v23, v205, v23, s[66:67]
	v_cndmask_b32_e64 v24, v205, v24, s[66:67]
	v_cndmask_b32_e64 v25, v205, v25, s[66:67]
	v_add_u32_e32 v242, 0, v249
	v_cmp_le_u32_e32 vcc, v242, v248
	s_nop 1
	v_cndmask_b32_e32 v86, v205, v86, vcc
	v_add_u32_e32 v242, 1, v249
	v_cmp_le_u32_e32 vcc, v242, v248
	s_nop 1
	v_cndmask_b32_e32 v87, v205, v87, vcc
	v_add_u32_e32 v242, 2, v249
	v_cmp_le_u32_e32 vcc, v242, v248
	s_nop 1
	v_cndmask_b32_e32 v88, v205, v88, vcc
	v_add_u32_e32 v242, 3, v249
	v_cmp_le_u32_e32 vcc, v242, v248
	s_nop 1
	v_cndmask_b32_e32 v89, v205, v89, vcc
	v_max3_f32 v238, v2, v3, v205
	v_max3_f32 v238, v238, v4, v5
	v_max3_f32 v238, v238, v6, v7
	v_max3_f32 v238, v238, v8, v9
	v_max3_f32 v238, v238, v10, v11
	v_max3_f32 v238, v238, v12, v13
	v_max3_f32 v238, v238, v14, v15
	v_max3_f32 v238, v238, v16, v17
	v_max3_f32 v238, v238, v18, v19
	v_max3_f32 v238, v238, v20, v21
	v_max3_f32 v238, v238, v22, v23
	v_max3_f32 v238, v238, v24, v25
	v_max3_f32 v238, v238, v26, v27
	v_max3_f32 v238, v238, v28, v29
	v_max3_f32 v238, v238, v30, v31
	v_max3_f32 v238, v238, v32, v33
	v_max3_f32 v238, v238, v86, v87
	v_max3_f32 v238, v238, v88, v89
	v_xor_b32_e32 v242, 16, v195
	v_lshlrev_b32_e32 v242, 2, v242
	ds_bpermute_b32 v242, v242, v238
	s_waitcnt lgkmcnt(0)
	v_max_f32_e32 v238, v238, v242
	v_xor_b32_e32 v242, 32, v195
	v_lshlrev_b32_e32 v242, 2, v242
	ds_bpermute_b32 v242, v242, v238
	s_waitcnt lgkmcnt(0)
	v_max_f32_e32 v238, v238, v242
	v_mul_f32_e32 v238, 0x3e000000, v238
	v_max_f32_e32 v238, v238, v85
	v_mul_f32_e32 v243, 0xbfb8aa3b, v238
	v_fmamk_f32 v2, v2, 0x3e38aa3b, v243
	v_fmamk_f32 v3, v3, 0x3e38aa3b, v243
	v_fmamk_f32 v4, v4, 0x3e38aa3b, v243
	v_fmamk_f32 v5, v5, 0x3e38aa3b, v243
	v_exp_f32_e32 v2, v2
	v_exp_f32_e32 v3, v3
	v_exp_f32_e32 v4, v4
	v_exp_f32_e32 v5, v5
	v_fmamk_f32 v6, v6, 0x3e38aa3b, v243
	v_fmamk_f32 v7, v7, 0x3e38aa3b, v243
	v_fmamk_f32 v8, v8, 0x3e38aa3b, v243
	v_fmamk_f32 v9, v9, 0x3e38aa3b, v243
	v_exp_f32_e32 v6, v6
	v_exp_f32_e32 v7, v7
	v_exp_f32_e32 v8, v8
	v_exp_f32_e32 v9, v9
	v_add_f32_e32 v239, 0, v2
	v_add_f32_e32 v239, v239, v3
	v_add_f32_e32 v239, v239, v4
	v_add_f32_e32 v239, v239, v5
	v_fmamk_f32 v10, v10, 0x3e38aa3b, v243
	v_fmamk_f32 v11, v11, 0x3e38aa3b, v243
	v_fmamk_f32 v12, v12, 0x3e38aa3b, v243
	v_fmamk_f32 v13, v13, 0x3e38aa3b, v243
	v_exp_f32_e32 v10, v10
	v_exp_f32_e32 v11, v11
	v_exp_f32_e32 v12, v12
	v_exp_f32_e32 v13, v13
	v_add_f32_e32 v239, v239, v6
	v_add_f32_e32 v239, v239, v7
	v_add_f32_e32 v239, v239, v8
	v_add_f32_e32 v239, v239, v9
	v_fmamk_f32 v14, v14, 0x3e38aa3b, v243
	v_fmamk_f32 v15, v15, 0x3e38aa3b, v243
	v_fmamk_f32 v16, v16, 0x3e38aa3b, v243
	v_fmamk_f32 v17, v17, 0x3e38aa3b, v243
	v_exp_f32_e32 v14, v14
	v_exp_f32_e32 v15, v15
	v_exp_f32_e32 v16, v16
	v_exp_f32_e32 v17, v17
	v_add_f32_e32 v239, v239, v10
	v_add_f32_e32 v239, v239, v11
	v_add_f32_e32 v239, v239, v12
	v_add_f32_e32 v239, v239, v13
	v_fmamk_f32 v18, v18, 0x3e38aa3b, v243
	v_fmamk_f32 v19, v19, 0x3e38aa3b, v243
	v_fmamk_f32 v20, v20, 0x3e38aa3b, v243
	v_fmamk_f32 v21, v21, 0x3e38aa3b, v243
	v_exp_f32_e32 v18, v18
	v_exp_f32_e32 v19, v19
	v_exp_f32_e32 v20, v20
	v_exp_f32_e32 v21, v21
	v_add_f32_e32 v239, v239, v14
	v_add_f32_e32 v239, v239, v15
	v_add_f32_e32 v239, v239, v16
	v_add_f32_e32 v239, v239, v17
	v_fmamk_f32 v22, v22, 0x3e38aa3b, v243
	v_fmamk_f32 v23, v23, 0x3e38aa3b, v243
	v_fmamk_f32 v24, v24, 0x3e38aa3b, v243
	v_fmamk_f32 v25, v25, 0x3e38aa3b, v243
	v_exp_f32_e32 v22, v22
	v_exp_f32_e32 v23, v23
	v_exp_f32_e32 v24, v24
	v_exp_f32_e32 v25, v25
	v_add_f32_e32 v239, v239, v18
	v_add_f32_e32 v239, v239, v19
	v_add_f32_e32 v239, v239, v20
	v_add_f32_e32 v239, v239, v21
	v_fmamk_f32 v26, v26, 0x3e38aa3b, v243
	v_fmamk_f32 v27, v27, 0x3e38aa3b, v243
	v_fmamk_f32 v28, v28, 0x3e38aa3b, v243
	v_fmamk_f32 v29, v29, 0x3e38aa3b, v243
	v_exp_f32_e32 v26, v26
	v_exp_f32_e32 v27, v27
	v_exp_f32_e32 v28, v28
	v_exp_f32_e32 v29, v29
	v_add_f32_e32 v239, v239, v22
	v_add_f32_e32 v239, v239, v23
	v_add_f32_e32 v239, v239, v24
	v_add_f32_e32 v239, v239, v25
	v_fmamk_f32 v30, v30, 0x3e38aa3b, v243
	v_fmamk_f32 v31, v31, 0x3e38aa3b, v243
	v_fmamk_f32 v32, v32, 0x3e38aa3b, v243
	v_fmamk_f32 v33, v33, 0x3e38aa3b, v243
	v_exp_f32_e32 v30, v30
	v_exp_f32_e32 v31, v31
	v_exp_f32_e32 v32, v32
	v_exp_f32_e32 v33, v33
	v_add_f32_e32 v239, v239, v26
	v_add_f32_e32 v239, v239, v27
	v_add_f32_e32 v239, v239, v28
	v_add_f32_e32 v239, v239, v29
	v_fmamk_f32 v86, v86, 0x3e38aa3b, v243
	v_fmamk_f32 v87, v87, 0x3e38aa3b, v243
	v_fmamk_f32 v88, v88, 0x3e38aa3b, v243
	v_fmamk_f32 v89, v89, 0x3e38aa3b, v243
	v_exp_f32_e32 v86, v86
	v_exp_f32_e32 v87, v87
	v_exp_f32_e32 v88, v88
	v_exp_f32_e32 v89, v89
	v_add_f32_e32 v239, v239, v30
	v_add_f32_e32 v239, v239, v31
	v_add_f32_e32 v239, v239, v32
	v_add_f32_e32 v239, v239, v33
	s_nop 0
	v_add_f32_e32 v239, v239, v86
	v_add_f32_e32 v239, v239, v87
	v_add_f32_e32 v239, v239, v88
	v_add_f32_e32 v239, v239, v89
	v_xor_b32_e32 v242, 16, v195
	v_lshlrev_b32_e32 v242, 2, v242
	ds_bpermute_b32 v242, v242, v239
	s_waitcnt lgkmcnt(0)
	v_add_f32_e32 v239, v239, v242
	v_xor_b32_e32 v242, 32, v195
	v_lshlrev_b32_e32 v242, 2, v242
	ds_bpermute_b32 v242, v242, v239
	s_waitcnt lgkmcnt(0)
	v_add_f32_e32 v239, v239, v242
	v_sub_f32_e32 v242, v85, v238
	v_mul_f32_e32 v242, 0x3fb8aa3b, v242
	v_exp_f32_e32 v242, v242
	s_nop 0
	v_add_f32_e32 v239, v239, v242
	v_rcp_f32_e32 v244, v239
	v_cvt_pk_bf16_f32 v218, v2, v3
	v_cvt_pk_bf16_f32 v219, v4, v5
	v_cvt_pk_bf16_f32 v220, v6, v7
	v_cvt_pk_bf16_f32 v221, v8, v9
	v_cvt_pk_bf16_f32 v222, v10, v11
	v_cvt_pk_bf16_f32 v223, v12, v13
	v_cvt_pk_bf16_f32 v224, v14, v15
	v_cvt_pk_bf16_f32 v225, v16, v17
	v_cvt_pk_bf16_f32 v226, v18, v19
	v_cvt_pk_bf16_f32 v227, v20, v21
	v_cvt_pk_bf16_f32 v228, v22, v23
	v_cvt_pk_bf16_f32 v229, v24, v25
	v_cvt_pk_bf16_f32 v230, v26, v27
	v_cvt_pk_bf16_f32 v231, v28, v29
	v_cvt_pk_bf16_f32 v232, v30, v31
	v_cvt_pk_bf16_f32 v233, v32, v33
	v_cvt_pk_bf16_f32 v234, v86, v87
	v_cvt_pk_bf16_f32 v235, v88, v89
	v_mov_b32_e32 v236, 0
	v_mov_b32_e32 v237, 0
	ds_read_b64 v[182:183], v245 offset:64
	ds_read_b64 v[184:185], v245 offset:96
	ds_read_b64 v[186:187], v245 offset:8512
	ds_read_b64 v[188:189], v245 offset:8544
	ds_read_b64 v[190:191], v245 offset:16960
	ds_read_b64 v[192:193], v245 offset:16992
	ds_read_b64 v[210:211], v245 offset:25408
	ds_read_b64 v[212:213], v245 offset:25440
	ds_read_b64 v[214:215], v245 offset:128
	ds_read_b64 v[216:217], v245 offset:160
	s_waitcnt lgkmcnt(8)
	v_mfma_f32_16x16x32_bf16 v[142:145], v[182:185], v[218:221], 0
	ds_read_b64 v[182:183], v245 offset:8576
	ds_read_b64 v[184:185], v245 offset:8608
	s_waitcnt lgkmcnt(8)
	v_mfma_f32_16x16x32_bf16 v[146:149], v[186:189], v[218:221], 0
	ds_read_b64 v[186:187], v245 offset:17024
	ds_read_b64 v[188:189], v245 offset:17056
	s_waitcnt lgkmcnt(8)
	v_mfma_f32_16x16x32_bf16 v[150:153], v[190:193], v[218:221], 0
	ds_read_b64 v[190:191], v245 offset:25472
	ds_read_b64 v[192:193], v245 offset:25504
	s_waitcnt lgkmcnt(8)
	v_mfma_f32_16x16x32_bf16 v[154:157], v[210:213], v[218:221], 0
	ds_read_b64 v[210:211], v245 offset:192
	ds_read_b64 v[212:213], v245 offset:224
	s_waitcnt lgkmcnt(8)
	v_mfma_f32_16x16x32_bf16 v[142:145], v[214:217], v[222:225], v[142:145]
	ds_read_b64 v[214:215], v245 offset:8640
	ds_read_b64 v[216:217], v245 offset:8672
	s_waitcnt lgkmcnt(8)
	v_mfma_f32_16x16x32_bf16 v[146:149], v[182:185], v[222:225], v[146:149]
	ds_read_b64 v[182:183], v245 offset:17088
	ds_read_b64 v[184:185], v245 offset:17120
	s_waitcnt lgkmcnt(8)
	v_mfma_f32_16x16x32_bf16 v[150:153], v[186:189], v[222:225], v[150:153]
	ds_read_b64 v[186:187], v245 offset:25536
	ds_read_b64 v[188:189], v245 offset:25568
	s_waitcnt lgkmcnt(8)
	v_mfma_f32_16x16x32_bf16 v[154:157], v[190:193], v[222:225], v[154:157]
	ds_read_b64 v[190:191], v245 offset:256
	ds_read_b64 v[192:193], v245 offset:288
	s_waitcnt lgkmcnt(8)
	v_mfma_f32_16x16x32_bf16 v[142:145], v[210:213], v[226:229], v[142:145]
	ds_read_b64 v[210:211], v245 offset:8704
	ds_read_b64 v[212:213], v245 offset:8736
	s_waitcnt lgkmcnt(8)
	v_mfma_f32_16x16x32_bf16 v[146:149], v[214:217], v[226:229], v[146:149]
	ds_read_b64 v[214:215], v245 offset:17152
	ds_read_b64 v[216:217], v245 offset:17184
	s_waitcnt lgkmcnt(8)
	v_mfma_f32_16x16x32_bf16 v[150:153], v[182:185], v[226:229], v[150:153]
	ds_read_b64 v[182:183], v245 offset:25600
	ds_read_b64 v[184:185], v245 offset:25632
	s_waitcnt lgkmcnt(8)
	v_mfma_f32_16x16x32_bf16 v[154:157], v[186:189], v[226:229], v[154:157]
	ds_read_b64 v[186:187], v245 offset:320
	ds_read_b64 v[188:189], v245 offset:320
	s_waitcnt lgkmcnt(8)
	v_mfma_f32_16x16x32_bf16 v[142:145], v[190:193], v[230:233], v[142:145]
	ds_read_b64 v[190:191], v245 offset:8768
	ds_read_b64 v[192:193], v245 offset:8768
	s_waitcnt lgkmcnt(8)
	v_mfma_f32_16x16x32_bf16 v[146:149], v[210:213], v[230:233], v[146:149]
	ds_read_b64 v[210:211], v245 offset:17216
	ds_read_b64 v[212:213], v245 offset:17216
	s_waitcnt lgkmcnt(8)
	v_mfma_f32_16x16x32_bf16 v[150:153], v[214:217], v[230:233], v[150:153]
	ds_read_b64 v[214:215], v245 offset:25664
	ds_read_b64 v[216:217], v245 offset:25664
	s_waitcnt lgkmcnt(8)
	v_mfma_f32_16x16x32_bf16 v[154:157], v[182:185], v[230:233], v[154:157]
	s_waitcnt lgkmcnt(6)
	v_mfma_f32_16x16x32_bf16 v[142:145], v[186:189], v[234:237], v[142:145]
	s_waitcnt lgkmcnt(4)
	v_mfma_f32_16x16x32_bf16 v[146:149], v[190:193], v[234:237], v[146:149]
	s_waitcnt lgkmcnt(2)
	v_mfma_f32_16x16x32_bf16 v[150:153], v[210:213], v[234:237], v[150:153]
	s_waitcnt lgkmcnt(0)
	v_mfma_f32_16x16x32_bf16 v[154:157], v[214:217], v[234:237], v[154:157]
	s_nop 7
	s_nop 1
	v_mul_f32_e32 v142, v244, v142
	v_mul_f32_e32 v143, v244, v143
	v_mul_f32_e32 v144, v244, v144
	v_mul_f32_e32 v145, v244, v145
	v_mul_f32_e32 v146, v244, v146
	v_mul_f32_e32 v147, v244, v147
	v_mul_f32_e32 v148, v244, v148
	v_mul_f32_e32 v149, v244, v149
	v_cvt_pk_bf16_f32 v240, v142, v143
	v_cvt_pk_bf16_f32 v241, v144, v145
	v_cvt_pk_bf16_f32 v242, v146, v147
	v_cvt_pk_bf16_f32 v243, v148, v149
	global_store_dwordx4 v[246:247], v[240:243], off
	s_nop 1
	v_mul_f32_e32 v150, v244, v150
	v_mul_f32_e32 v151, v244, v151
	v_mul_f32_e32 v152, v244, v152
	v_mul_f32_e32 v153, v244, v153
	v_mul_f32_e32 v154, v244, v154
	v_mul_f32_e32 v155, v244, v155
	v_mul_f32_e32 v156, v244, v156
	v_mul_f32_e32 v157, v244, v157
	v_cvt_pk_bf16_f32 v240, v150, v151
	v_cvt_pk_bf16_f32 v241, v152, v153
	v_cvt_pk_bf16_f32 v242, v154, v155
	v_cvt_pk_bf16_f32 v243, v156, v157
	global_store_dwordx4 v[246:247], v[240:243], off offset:64
	v_lshl_add_u64 v[246:247], v[246:247], 0, s[8:9]
	s_waitcnt vmcnt(2)
	ds_read_b128 v[106:109], v118 offset:6912
	ds_read_b128 v[110:113], v118 offset:6976
	ds_read_b128 v[114:117], v118 offset:9216
	ds_read_b128 v[128:131], v118 offset:9280
	ds_read_b128 v[132:135], v118 offset:11520
	ds_read_b128 v[120:123], v118 offset:11584
	s_waitcnt lgkmcnt(5)
	v_mfma_f32_16x16x32_bf16 v[2:5], v[106:109], v[98:101], 0
	ds_read_b128 v[106:109], v118 offset:13824
	s_waitcnt lgkmcnt(5)
	v_mfma_f32_16x16x32_bf16 v[2:5], v[110:113], v[102:105], v[2:5]
	ds_read_b128 v[110:113], v118 offset:13888
	s_waitcnt lgkmcnt(5)
	v_mfma_f32_16x16x32_bf16 v[6:9], v[114:117], v[98:101], 0
	ds_read_b128 v[114:117], v118 offset:16128
	s_waitcnt lgkmcnt(5)
	v_mfma_f32_16x16x32_bf16 v[6:9], v[128:131], v[102:105], v[6:9]
	ds_read_b128 v[128:131], v118 offset:16192
	s_waitcnt lgkmcnt(5)
	v_mfma_f32_16x16x32_bf16 v[10:13], v[132:135], v[98:101], 0
	ds_read_b128 v[132:135], v118 offset:18432
	s_waitcnt lgkmcnt(5)
	v_mfma_f32_16x16x32_bf16 v[10:13], v[120:123], v[102:105], v[10:13]
	ds_read_b128 v[120:123], v118 offset:18496
	s_waitcnt lgkmcnt(5)
	v_mfma_f32_16x16x32_bf16 v[14:17], v[106:109], v[98:101], 0
	ds_read_b128 v[106:109], v118 offset:20736
	s_waitcnt lgkmcnt(5)
	v_mfma_f32_16x16x32_bf16 v[14:17], v[110:113], v[102:105], v[14:17]
	ds_read_b128 v[110:113], v118 offset:20800
	s_waitcnt lgkmcnt(5)
	v_mfma_f32_16x16x32_bf16 v[18:21], v[114:117], v[98:101], 0
	ds_read_b128 v[114:117], v118 offset:23040
	s_waitcnt lgkmcnt(5)
	v_mfma_f32_16x16x32_bf16 v[18:21], v[128:131], v[102:105], v[18:21]
	ds_read_b128 v[128:131], v118 offset:23104
	s_waitcnt lgkmcnt(5)
	v_mfma_f32_16x16x32_bf16 v[22:25], v[132:135], v[98:101], 0
	ds_read_b128 v[132:135], v118 offset:25344
	s_waitcnt lgkmcnt(5)
	v_mfma_f32_16x16x32_bf16 v[22:25], v[120:123], v[102:105], v[22:25]
	ds_read_b128 v[120:123], v118 offset:25408
	s_waitcnt lgkmcnt(5)
	v_mfma_f32_16x16x32_bf16 v[26:29], v[106:109], v[98:101], 0
	s_waitcnt lgkmcnt(4)
	v_mfma_f32_16x16x32_bf16 v[26:29], v[110:113], v[102:105], v[26:29]
	s_waitcnt lgkmcnt(3)
	v_mfma_f32_16x16x32_bf16 v[30:33], v[114:117], v[98:101], 0
	s_waitcnt lgkmcnt(2)
	v_mfma_f32_16x16x32_bf16 v[30:33], v[128:131], v[102:105], v[30:33]
	s_waitcnt lgkmcnt(1)
	v_mfma_f32_16x16x32_bf16 v[86:89], v[132:135], v[98:101], 0
	s_waitcnt lgkmcnt(0)
	v_mfma_f32_16x16x32_bf16 v[86:89], v[120:123], v[102:105], v[86:89]
	v_lshl_add_u64 v[240:241], v[246:247], 0, s[8:9]
	global_load_dwordx4 v[90:93], v[240:241], off
	global_load_dwordx4 v[94:97], v[240:241], off offset:64
	v_add_u32_e32 v242, 0, v249
	v_cmp_gt_u32_e32 vcc, v242, v248
	s_nop 1
	s_and_b64 vcc, vcc, s[66:67]
	s_nop 0
	v_cndmask_b32_e32 v2, v205, v2, vcc
	v_add_u32_e32 v242, 1, v249
	v_cmp_gt_u32_e32 vcc, v242, v248
	s_nop 1
	s_and_b64 vcc, vcc, s[66:67]
	s_nop 0
	v_cndmask_b32_e32 v3, v205, v3, vcc
	v_add_u32_e32 v242, 2, v249
	v_cmp_gt_u32_e32 vcc, v242, v248
	s_nop 1
	s_and_b64 vcc, vcc, s[66:67]
	s_nop 0
	v_cndmask_b32_e32 v4, v205, v4, vcc
	v_add_u32_e32 v242, 3, v249
	v_cmp_gt_u32_e32 vcc, v242, v248
	s_nop 1
	s_and_b64 vcc, vcc, s[66:67]
	s_nop 0
	v_cndmask_b32_e32 v5, v205, v5, vcc
	v_cndmask_b32_e64 v6, v205, v6, s[66:67]
	v_cndmask_b32_e64 v7, v205, v7, s[66:67]
	v_cndmask_b32_e64 v8, v205, v8, s[66:67]
	v_cndmask_b32_e64 v9, v205, v9, s[66:67]
	v_cndmask_b32_e64 v10, v205, v10, s[66:67]
	v_cndmask_b32_e64 v11, v205, v11, s[66:67]
	v_cndmask_b32_e64 v12, v205, v12, s[66:67]
	v_cndmask_b32_e64 v13, v205, v13, s[66:67]
	v_cndmask_b32_e64 v14, v205, v14, s[66:67]
	v_cndmask_b32_e64 v15, v205, v15, s[66:67]
	v_cndmask_b32_e64 v16, v205, v16, s[66:67]
	v_cndmask_b32_e64 v17, v205, v17, s[66:67]
	v_cndmask_b32_e64 v18, v205, v18, s[66:67]
	v_cndmask_b32_e64 v19, v205, v19, s[66:67]
	v_cndmask_b32_e64 v20, v205, v20, s[66:67]
	v_cndmask_b32_e64 v21, v205, v21, s[66:67]
	v_add_u32_e32 v242, 0, v249
	v_cmp_le_u32_e32 vcc, v242, v248
	s_nop 1
	v_cndmask_b32_e32 v86, v205, v86, vcc
	v_add_u32_e32 v242, 1, v249
	v_cmp_le_u32_e32 vcc, v242, v248
	s_nop 1
	v_cndmask_b32_e32 v87, v205, v87, vcc
	v_add_u32_e32 v242, 2, v249
	v_cmp_le_u32_e32 vcc, v242, v248
	s_nop 1
	v_cndmask_b32_e32 v88, v205, v88, vcc
	v_add_u32_e32 v242, 3, v249
	v_cmp_le_u32_e32 vcc, v242, v248
	s_nop 1
	v_cndmask_b32_e32 v89, v205, v89, vcc
	v_max3_f32 v238, v2, v3, v205
	v_max3_f32 v238, v238, v4, v5
	v_max3_f32 v238, v238, v6, v7
	v_max3_f32 v238, v238, v8, v9
	v_max3_f32 v238, v238, v10, v11
	v_max3_f32 v238, v238, v12, v13
	v_max3_f32 v238, v238, v14, v15
	v_max3_f32 v238, v238, v16, v17
	v_max3_f32 v238, v238, v18, v19
	v_max3_f32 v238, v238, v20, v21
	v_max3_f32 v238, v238, v22, v23
	v_max3_f32 v238, v238, v24, v25
	v_max3_f32 v238, v238, v26, v27
	v_max3_f32 v238, v238, v28, v29
	v_max3_f32 v238, v238, v30, v31
	v_max3_f32 v238, v238, v32, v33
	v_max3_f32 v238, v238, v86, v87
	v_max3_f32 v238, v238, v88, v89
	v_xor_b32_e32 v242, 16, v195
	v_lshlrev_b32_e32 v242, 2, v242
	ds_bpermute_b32 v242, v242, v238
	s_waitcnt lgkmcnt(0)
	v_max_f32_e32 v238, v238, v242
	v_xor_b32_e32 v242, 32, v195
	v_lshlrev_b32_e32 v242, 2, v242
	ds_bpermute_b32 v242, v242, v238
	s_waitcnt lgkmcnt(0)
	v_max_f32_e32 v238, v238, v242
	v_mul_f32_e32 v238, 0x3e000000, v238
	v_max_f32_e32 v238, v238, v85
	v_mul_f32_e32 v243, 0xbfb8aa3b, v238
	v_fmamk_f32 v2, v2, 0x3e38aa3b, v243
	v_fmamk_f32 v3, v3, 0x3e38aa3b, v243
	v_fmamk_f32 v4, v4, 0x3e38aa3b, v243
	v_fmamk_f32 v5, v5, 0x3e38aa3b, v243
	v_exp_f32_e32 v2, v2
	v_exp_f32_e32 v3, v3
	v_exp_f32_e32 v4, v4
	v_exp_f32_e32 v5, v5
	v_fmamk_f32 v6, v6, 0x3e38aa3b, v243
	v_fmamk_f32 v7, v7, 0x3e38aa3b, v243
	v_fmamk_f32 v8, v8, 0x3e38aa3b, v243
	v_fmamk_f32 v9, v9, 0x3e38aa3b, v243
	v_exp_f32_e32 v6, v6
	v_exp_f32_e32 v7, v7
	v_exp_f32_e32 v8, v8
	v_exp_f32_e32 v9, v9
	v_add_f32_e32 v239, 0, v2
	v_add_f32_e32 v239, v239, v3
	v_add_f32_e32 v239, v239, v4
	v_add_f32_e32 v239, v239, v5
	v_fmamk_f32 v10, v10, 0x3e38aa3b, v243
	v_fmamk_f32 v11, v11, 0x3e38aa3b, v243
	v_fmamk_f32 v12, v12, 0x3e38aa3b, v243
	v_fmamk_f32 v13, v13, 0x3e38aa3b, v243
	v_exp_f32_e32 v10, v10
	v_exp_f32_e32 v11, v11
	v_exp_f32_e32 v12, v12
	v_exp_f32_e32 v13, v13
	v_add_f32_e32 v239, v239, v6
	v_add_f32_e32 v239, v239, v7
	v_add_f32_e32 v239, v239, v8
	v_add_f32_e32 v239, v239, v9
	v_fmamk_f32 v14, v14, 0x3e38aa3b, v243
	v_fmamk_f32 v15, v15, 0x3e38aa3b, v243
	v_fmamk_f32 v16, v16, 0x3e38aa3b, v243
	v_fmamk_f32 v17, v17, 0x3e38aa3b, v243
	v_exp_f32_e32 v14, v14
	v_exp_f32_e32 v15, v15
	v_exp_f32_e32 v16, v16
	v_exp_f32_e32 v17, v17
	v_add_f32_e32 v239, v239, v10
	v_add_f32_e32 v239, v239, v11
	v_add_f32_e32 v239, v239, v12
	v_add_f32_e32 v239, v239, v13
	v_fmamk_f32 v18, v18, 0x3e38aa3b, v243
	v_fmamk_f32 v19, v19, 0x3e38aa3b, v243
	v_fmamk_f32 v20, v20, 0x3e38aa3b, v243
	v_fmamk_f32 v21, v21, 0x3e38aa3b, v243
	v_exp_f32_e32 v18, v18
	v_exp_f32_e32 v19, v19
	v_exp_f32_e32 v20, v20
	v_exp_f32_e32 v21, v21
	v_add_f32_e32 v239, v239, v14
	v_add_f32_e32 v239, v239, v15
	v_add_f32_e32 v239, v239, v16
	v_add_f32_e32 v239, v239, v17
	v_fmamk_f32 v22, v22, 0x3e38aa3b, v243
	v_fmamk_f32 v23, v23, 0x3e38aa3b, v243
	v_fmamk_f32 v24, v24, 0x3e38aa3b, v243
	v_fmamk_f32 v25, v25, 0x3e38aa3b, v243
	v_exp_f32_e32 v22, v22
	v_exp_f32_e32 v23, v23
	v_exp_f32_e32 v24, v24
	v_exp_f32_e32 v25, v25
	v_add_f32_e32 v239, v239, v18
	v_add_f32_e32 v239, v239, v19
	v_add_f32_e32 v239, v239, v20
	v_add_f32_e32 v239, v239, v21
	v_fmamk_f32 v26, v26, 0x3e38aa3b, v243
	v_fmamk_f32 v27, v27, 0x3e38aa3b, v243
	v_fmamk_f32 v28, v28, 0x3e38aa3b, v243
	v_fmamk_f32 v29, v29, 0x3e38aa3b, v243
	v_exp_f32_e32 v26, v26
	v_exp_f32_e32 v27, v27
	v_exp_f32_e32 v28, v28
	v_exp_f32_e32 v29, v29
	v_add_f32_e32 v239, v239, v22
	v_add_f32_e32 v239, v239, v23
	v_add_f32_e32 v239, v239, v24
	v_add_f32_e32 v239, v239, v25
	v_fmamk_f32 v30, v30, 0x3e38aa3b, v243
	v_fmamk_f32 v31, v31, 0x3e38aa3b, v243
	v_fmamk_f32 v32, v32, 0x3e38aa3b, v243
	v_fmamk_f32 v33, v33, 0x3e38aa3b, v243
	v_exp_f32_e32 v30, v30
	v_exp_f32_e32 v31, v31
	v_exp_f32_e32 v32, v32
	v_exp_f32_e32 v33, v33
	v_add_f32_e32 v239, v239, v26
	v_add_f32_e32 v239, v239, v27
	v_add_f32_e32 v239, v239, v28
	v_add_f32_e32 v239, v239, v29
	v_fmamk_f32 v86, v86, 0x3e38aa3b, v243
	v_fmamk_f32 v87, v87, 0x3e38aa3b, v243
	v_fmamk_f32 v88, v88, 0x3e38aa3b, v243
	v_fmamk_f32 v89, v89, 0x3e38aa3b, v243
	v_exp_f32_e32 v86, v86
	v_exp_f32_e32 v87, v87
	v_exp_f32_e32 v88, v88
	v_exp_f32_e32 v89, v89
	v_add_f32_e32 v239, v239, v30
	v_add_f32_e32 v239, v239, v31
	v_add_f32_e32 v239, v239, v32
	v_add_f32_e32 v239, v239, v33
	s_nop 0
	v_add_f32_e32 v239, v239, v86
	v_add_f32_e32 v239, v239, v87
	v_add_f32_e32 v239, v239, v88
	v_add_f32_e32 v239, v239, v89
	v_xor_b32_e32 v242, 16, v195
	v_lshlrev_b32_e32 v242, 2, v242
	ds_bpermute_b32 v242, v242, v239
	s_waitcnt lgkmcnt(0)
	v_add_f32_e32 v239, v239, v242
	v_xor_b32_e32 v242, 32, v195
	v_lshlrev_b32_e32 v242, 2, v242
	ds_bpermute_b32 v242, v242, v239
	s_waitcnt lgkmcnt(0)
	v_add_f32_e32 v239, v239, v242
	v_sub_f32_e32 v242, v85, v238
	v_mul_f32_e32 v242, 0x3fb8aa3b, v242
	v_exp_f32_e32 v242, v242
	s_nop 0
	v_add_f32_e32 v239, v239, v242
	v_rcp_f32_e32 v244, v239
	v_cvt_pk_bf16_f32 v218, v2, v3
	v_cvt_pk_bf16_f32 v219, v4, v5
	v_cvt_pk_bf16_f32 v220, v6, v7
	v_cvt_pk_bf16_f32 v221, v8, v9
	v_cvt_pk_bf16_f32 v222, v10, v11
	v_cvt_pk_bf16_f32 v223, v12, v13
	v_cvt_pk_bf16_f32 v224, v14, v15
	v_cvt_pk_bf16_f32 v225, v16, v17
	v_cvt_pk_bf16_f32 v226, v18, v19
	v_cvt_pk_bf16_f32 v227, v20, v21
	v_cvt_pk_bf16_f32 v228, v22, v23
	v_cvt_pk_bf16_f32 v229, v24, v25
	v_cvt_pk_bf16_f32 v230, v26, v27
	v_cvt_pk_bf16_f32 v231, v28, v29
	v_cvt_pk_bf16_f32 v232, v30, v31
	v_cvt_pk_bf16_f32 v233, v32, v33
	v_cvt_pk_bf16_f32 v234, v86, v87
	v_cvt_pk_bf16_f32 v235, v88, v89
	v_mov_b32_e32 v236, 0
	v_mov_b32_e32 v237, 0
	ds_read_b64 v[182:183], v245 offset:96
	ds_read_b64 v[184:185], v245 offset:128
	ds_read_b64 v[186:187], v245 offset:8544
	ds_read_b64 v[188:189], v245 offset:8576
	ds_read_b64 v[190:191], v245 offset:16992
	ds_read_b64 v[192:193], v245 offset:17024
	ds_read_b64 v[210:211], v245 offset:25440
	ds_read_b64 v[212:213], v245 offset:25472
	ds_read_b64 v[214:215], v245 offset:160
	ds_read_b64 v[216:217], v245 offset:192
	s_waitcnt lgkmcnt(8)
	v_mfma_f32_16x16x32_bf16 v[142:145], v[182:185], v[218:221], 0
	ds_read_b64 v[182:183], v245 offset:8608
	ds_read_b64 v[184:185], v245 offset:8640
	s_waitcnt lgkmcnt(8)
	v_mfma_f32_16x16x32_bf16 v[146:149], v[186:189], v[218:221], 0
	ds_read_b64 v[186:187], v245 offset:17056
	ds_read_b64 v[188:189], v245 offset:17088
	s_waitcnt lgkmcnt(8)
	v_mfma_f32_16x16x32_bf16 v[150:153], v[190:193], v[218:221], 0
	ds_read_b64 v[190:191], v245 offset:25504
	ds_read_b64 v[192:193], v245 offset:25536
	s_waitcnt lgkmcnt(8)
	v_mfma_f32_16x16x32_bf16 v[154:157], v[210:213], v[218:221], 0
	ds_read_b64 v[210:211], v245 offset:224
	ds_read_b64 v[212:213], v245 offset:256
	s_waitcnt lgkmcnt(8)
	v_mfma_f32_16x16x32_bf16 v[142:145], v[214:217], v[222:225], v[142:145]
	ds_read_b64 v[214:215], v245 offset:8672
	ds_read_b64 v[216:217], v245 offset:8704
	s_waitcnt lgkmcnt(8)
	v_mfma_f32_16x16x32_bf16 v[146:149], v[182:185], v[222:225], v[146:149]
	ds_read_b64 v[182:183], v245 offset:17120
	ds_read_b64 v[184:185], v245 offset:17152
	s_waitcnt lgkmcnt(8)
	v_mfma_f32_16x16x32_bf16 v[150:153], v[186:189], v[222:225], v[150:153]
	ds_read_b64 v[186:187], v245 offset:25568
	ds_read_b64 v[188:189], v245 offset:25600
	s_waitcnt lgkmcnt(8)
	v_mfma_f32_16x16x32_bf16 v[154:157], v[190:193], v[222:225], v[154:157]
	ds_read_b64 v[190:191], v245 offset:288
	ds_read_b64 v[192:193], v245 offset:320
	s_waitcnt lgkmcnt(8)
	v_mfma_f32_16x16x32_bf16 v[142:145], v[210:213], v[226:229], v[142:145]
	ds_read_b64 v[210:211], v245 offset:8736
	ds_read_b64 v[212:213], v245 offset:8768
	s_waitcnt lgkmcnt(8)
	v_mfma_f32_16x16x32_bf16 v[146:149], v[214:217], v[226:229], v[146:149]
	ds_read_b64 v[214:215], v245 offset:17184
	ds_read_b64 v[216:217], v245 offset:17216
	s_waitcnt lgkmcnt(8)
	v_mfma_f32_16x16x32_bf16 v[150:153], v[182:185], v[226:229], v[150:153]
	ds_read_b64 v[182:183], v245 offset:25632
	ds_read_b64 v[184:185], v245 offset:25664
	s_waitcnt lgkmcnt(8)
	v_mfma_f32_16x16x32_bf16 v[154:157], v[186:189], v[226:229], v[154:157]
	ds_read_b64 v[186:187], v245 offset:352
	ds_read_b64 v[188:189], v245 offset:352
	s_waitcnt lgkmcnt(8)
	v_mfma_f32_16x16x32_bf16 v[142:145], v[190:193], v[230:233], v[142:145]
	ds_read_b64 v[190:191], v245 offset:8800
	ds_read_b64 v[192:193], v245 offset:8800
	s_waitcnt lgkmcnt(8)
	v_mfma_f32_16x16x32_bf16 v[146:149], v[210:213], v[230:233], v[146:149]
	ds_read_b64 v[210:211], v245 offset:17248
	ds_read_b64 v[212:213], v245 offset:17248
	s_waitcnt lgkmcnt(8)
	v_mfma_f32_16x16x32_bf16 v[150:153], v[214:217], v[230:233], v[150:153]
	ds_read_b64 v[214:215], v245 offset:25696
	ds_read_b64 v[216:217], v245 offset:25696
	s_waitcnt lgkmcnt(8)
	v_mfma_f32_16x16x32_bf16 v[154:157], v[182:185], v[230:233], v[154:157]
	s_waitcnt lgkmcnt(6)
	v_mfma_f32_16x16x32_bf16 v[142:145], v[186:189], v[234:237], v[142:145]
	s_waitcnt lgkmcnt(4)
	v_mfma_f32_16x16x32_bf16 v[146:149], v[190:193], v[234:237], v[146:149]
	s_waitcnt lgkmcnt(2)
	v_mfma_f32_16x16x32_bf16 v[150:153], v[210:213], v[234:237], v[150:153]
	s_waitcnt lgkmcnt(0)
	v_mfma_f32_16x16x32_bf16 v[154:157], v[214:217], v[234:237], v[154:157]
	s_nop 7
	s_nop 1
	v_mul_f32_e32 v142, v244, v142
	v_mul_f32_e32 v143, v244, v143
	v_mul_f32_e32 v144, v244, v144
	v_mul_f32_e32 v145, v244, v145
	v_mul_f32_e32 v146, v244, v146
	v_mul_f32_e32 v147, v244, v147
	v_mul_f32_e32 v148, v244, v148
	v_mul_f32_e32 v149, v244, v149
	v_cvt_pk_bf16_f32 v240, v142, v143
	v_cvt_pk_bf16_f32 v241, v144, v145
	v_cvt_pk_bf16_f32 v242, v146, v147
	v_cvt_pk_bf16_f32 v243, v148, v149
	global_store_dwordx4 v[246:247], v[240:243], off
	s_nop 1
	v_mul_f32_e32 v150, v244, v150
	v_mul_f32_e32 v151, v244, v151
	v_mul_f32_e32 v152, v244, v152
	v_mul_f32_e32 v153, v244, v153
	v_mul_f32_e32 v154, v244, v154
	v_mul_f32_e32 v155, v244, v155
	v_mul_f32_e32 v156, v244, v156
	v_mul_f32_e32 v157, v244, v157
	v_cvt_pk_bf16_f32 v240, v150, v151
	v_cvt_pk_bf16_f32 v241, v152, v153
	v_cvt_pk_bf16_f32 v242, v154, v155
	v_cvt_pk_bf16_f32 v243, v156, v157
	global_store_dwordx4 v[246:247], v[240:243], off offset:64
	v_lshl_add_u64 v[246:247], v[246:247], 0, s[8:9]
	s_waitcnt vmcnt(2)
	ds_read_b128 v[106:109], v118 offset:9216
	ds_read_b128 v[110:113], v118 offset:9280
	ds_read_b128 v[114:117], v118 offset:11520
	ds_read_b128 v[128:131], v118 offset:11584
	ds_read_b128 v[132:135], v118 offset:13824
	ds_read_b128 v[120:123], v118 offset:13888
	s_waitcnt lgkmcnt(5)
	v_mfma_f32_16x16x32_bf16 v[2:5], v[106:109], v[90:93], 0
	ds_read_b128 v[106:109], v118 offset:16128
	s_waitcnt lgkmcnt(5)
	v_mfma_f32_16x16x32_bf16 v[2:5], v[110:113], v[94:97], v[2:5]
	ds_read_b128 v[110:113], v118 offset:16192
	s_waitcnt lgkmcnt(5)
	v_mfma_f32_16x16x32_bf16 v[6:9], v[114:117], v[90:93], 0
	ds_read_b128 v[114:117], v118 offset:18432
	s_waitcnt lgkmcnt(5)
	v_mfma_f32_16x16x32_bf16 v[6:9], v[128:131], v[94:97], v[6:9]
	ds_read_b128 v[128:131], v118 offset:18496
	s_waitcnt lgkmcnt(5)
	v_mfma_f32_16x16x32_bf16 v[10:13], v[132:135], v[90:93], 0
	ds_read_b128 v[132:135], v118 offset:20736
	s_waitcnt lgkmcnt(5)
	v_mfma_f32_16x16x32_bf16 v[10:13], v[120:123], v[94:97], v[10:13]
	ds_read_b128 v[120:123], v118 offset:20800
	s_waitcnt lgkmcnt(5)
	v_mfma_f32_16x16x32_bf16 v[14:17], v[106:109], v[90:93], 0
	ds_read_b128 v[106:109], v118 offset:23040
	s_waitcnt lgkmcnt(5)
	v_mfma_f32_16x16x32_bf16 v[14:17], v[110:113], v[94:97], v[14:17]
	ds_read_b128 v[110:113], v118 offset:23104
	s_waitcnt lgkmcnt(5)
	v_mfma_f32_16x16x32_bf16 v[18:21], v[114:117], v[90:93], 0
	ds_read_b128 v[114:117], v118 offset:25344
	s_waitcnt lgkmcnt(5)
	v_mfma_f32_16x16x32_bf16 v[18:21], v[128:131], v[94:97], v[18:21]
	ds_read_b128 v[128:131], v118 offset:25408
	s_waitcnt lgkmcnt(5)
	v_mfma_f32_16x16x32_bf16 v[22:25], v[132:135], v[90:93], 0
	ds_read_b128 v[132:135], v118 offset:27648
	s_waitcnt lgkmcnt(5)
	v_mfma_f32_16x16x32_bf16 v[22:25], v[120:123], v[94:97], v[22:25]
	ds_read_b128 v[120:123], v118 offset:27712
	s_waitcnt lgkmcnt(5)
	v_mfma_f32_16x16x32_bf16 v[26:29], v[106:109], v[90:93], 0
	s_waitcnt lgkmcnt(4)
	v_mfma_f32_16x16x32_bf16 v[26:29], v[110:113], v[94:97], v[26:29]
	s_waitcnt lgkmcnt(3)
	v_mfma_f32_16x16x32_bf16 v[30:33], v[114:117], v[90:93], 0
	s_waitcnt lgkmcnt(2)
	v_mfma_f32_16x16x32_bf16 v[30:33], v[128:131], v[94:97], v[30:33]
	s_waitcnt lgkmcnt(1)
	v_mfma_f32_16x16x32_bf16 v[86:89], v[132:135], v[90:93], 0
	s_waitcnt lgkmcnt(0)
	v_mfma_f32_16x16x32_bf16 v[86:89], v[120:123], v[94:97], v[86:89]
	v_lshl_add_u64 v[240:241], v[246:247], 0, s[8:9]
	global_load_dwordx4 v[98:101], v[240:241], off
	global_load_dwordx4 v[102:105], v[240:241], off offset:64
	v_add_u32_e32 v242, 0, v249
	v_cmp_gt_u32_e32 vcc, v242, v248
	s_nop 1
	s_and_b64 vcc, vcc, s[66:67]
	s_nop 0
	v_cndmask_b32_e32 v2, v205, v2, vcc
	v_add_u32_e32 v242, 1, v249
	v_cmp_gt_u32_e32 vcc, v242, v248
	s_nop 1
	s_and_b64 vcc, vcc, s[66:67]
	s_nop 0
	v_cndmask_b32_e32 v3, v205, v3, vcc
	v_add_u32_e32 v242, 2, v249
	v_cmp_gt_u32_e32 vcc, v242, v248
	s_nop 1
	s_and_b64 vcc, vcc, s[66:67]
	s_nop 0
	v_cndmask_b32_e32 v4, v205, v4, vcc
	v_add_u32_e32 v242, 3, v249
	v_cmp_gt_u32_e32 vcc, v242, v248
	s_nop 1
	s_and_b64 vcc, vcc, s[66:67]
	s_nop 0
	v_cndmask_b32_e32 v5, v205, v5, vcc
	v_cndmask_b32_e64 v6, v205, v6, s[66:67]
	v_cndmask_b32_e64 v7, v205, v7, s[66:67]
	v_cndmask_b32_e64 v8, v205, v8, s[66:67]
	v_cndmask_b32_e64 v9, v205, v9, s[66:67]
	v_cndmask_b32_e64 v10, v205, v10, s[66:67]
	v_cndmask_b32_e64 v11, v205, v11, s[66:67]
	v_cndmask_b32_e64 v12, v205, v12, s[66:67]
	v_cndmask_b32_e64 v13, v205, v13, s[66:67]
	v_cndmask_b32_e64 v14, v205, v14, s[66:67]
	v_cndmask_b32_e64 v15, v205, v15, s[66:67]
	v_cndmask_b32_e64 v16, v205, v16, s[66:67]
	v_cndmask_b32_e64 v17, v205, v17, s[66:67]
	v_add_u32_e32 v242, 0, v249
	v_cmp_le_u32_e32 vcc, v242, v248
	s_nop 1
	v_cndmask_b32_e32 v86, v205, v86, vcc
	v_add_u32_e32 v242, 1, v249
	v_cmp_le_u32_e32 vcc, v242, v248
	s_nop 1
	v_cndmask_b32_e32 v87, v205, v87, vcc
	v_add_u32_e32 v242, 2, v249
	v_cmp_le_u32_e32 vcc, v242, v248
	s_nop 1
	v_cndmask_b32_e32 v88, v205, v88, vcc
	v_add_u32_e32 v242, 3, v249
	v_cmp_le_u32_e32 vcc, v242, v248
	s_nop 1
	v_cndmask_b32_e32 v89, v205, v89, vcc
	v_max3_f32 v238, v2, v3, v205
	v_max3_f32 v238, v238, v4, v5
	v_max3_f32 v238, v238, v6, v7
	v_max3_f32 v238, v238, v8, v9
	v_max3_f32 v238, v238, v10, v11
	v_max3_f32 v238, v238, v12, v13
	v_max3_f32 v238, v238, v14, v15
	v_max3_f32 v238, v238, v16, v17
	v_max3_f32 v238, v238, v18, v19
	v_max3_f32 v238, v238, v20, v21
	v_max3_f32 v238, v238, v22, v23
	v_max3_f32 v238, v238, v24, v25
	v_max3_f32 v238, v238, v26, v27
	v_max3_f32 v238, v238, v28, v29
	v_max3_f32 v238, v238, v30, v31
	v_max3_f32 v238, v238, v32, v33
	v_max3_f32 v238, v238, v86, v87
	v_max3_f32 v238, v238, v88, v89
	v_xor_b32_e32 v242, 16, v195
	v_lshlrev_b32_e32 v242, 2, v242
	ds_bpermute_b32 v242, v242, v238
	s_waitcnt lgkmcnt(0)
	v_max_f32_e32 v238, v238, v242
	v_xor_b32_e32 v242, 32, v195
	v_lshlrev_b32_e32 v242, 2, v242
	ds_bpermute_b32 v242, v242, v238
	s_waitcnt lgkmcnt(0)
	v_max_f32_e32 v238, v238, v242
	v_mul_f32_e32 v238, 0x3e000000, v238
	v_max_f32_e32 v238, v238, v85
	v_mul_f32_e32 v243, 0xbfb8aa3b, v238
	v_fmamk_f32 v2, v2, 0x3e38aa3b, v243
	v_fmamk_f32 v3, v3, 0x3e38aa3b, v243
	v_fmamk_f32 v4, v4, 0x3e38aa3b, v243
	v_fmamk_f32 v5, v5, 0x3e38aa3b, v243
	v_exp_f32_e32 v2, v2
	v_exp_f32_e32 v3, v3
	v_exp_f32_e32 v4, v4
	v_exp_f32_e32 v5, v5
	v_fmamk_f32 v6, v6, 0x3e38aa3b, v243
	v_fmamk_f32 v7, v7, 0x3e38aa3b, v243
	v_fmamk_f32 v8, v8, 0x3e38aa3b, v243
	v_fmamk_f32 v9, v9, 0x3e38aa3b, v243
	v_exp_f32_e32 v6, v6
	v_exp_f32_e32 v7, v7
	v_exp_f32_e32 v8, v8
	v_exp_f32_e32 v9, v9
	v_add_f32_e32 v239, 0, v2
	v_add_f32_e32 v239, v239, v3
	v_add_f32_e32 v239, v239, v4
	v_add_f32_e32 v239, v239, v5
	v_fmamk_f32 v10, v10, 0x3e38aa3b, v243
	v_fmamk_f32 v11, v11, 0x3e38aa3b, v243
	v_fmamk_f32 v12, v12, 0x3e38aa3b, v243
	v_fmamk_f32 v13, v13, 0x3e38aa3b, v243
	v_exp_f32_e32 v10, v10
	v_exp_f32_e32 v11, v11
	v_exp_f32_e32 v12, v12
	v_exp_f32_e32 v13, v13
	v_add_f32_e32 v239, v239, v6
	v_add_f32_e32 v239, v239, v7
	v_add_f32_e32 v239, v239, v8
	v_add_f32_e32 v239, v239, v9
	v_fmamk_f32 v14, v14, 0x3e38aa3b, v243
	v_fmamk_f32 v15, v15, 0x3e38aa3b, v243
	v_fmamk_f32 v16, v16, 0x3e38aa3b, v243
	v_fmamk_f32 v17, v17, 0x3e38aa3b, v243
	v_exp_f32_e32 v14, v14
	v_exp_f32_e32 v15, v15
	v_exp_f32_e32 v16, v16
	v_exp_f32_e32 v17, v17
	v_add_f32_e32 v239, v239, v10
	v_add_f32_e32 v239, v239, v11
	v_add_f32_e32 v239, v239, v12
	v_add_f32_e32 v239, v239, v13
	v_fmamk_f32 v18, v18, 0x3e38aa3b, v243
	v_fmamk_f32 v19, v19, 0x3e38aa3b, v243
	v_fmamk_f32 v20, v20, 0x3e38aa3b, v243
	v_fmamk_f32 v21, v21, 0x3e38aa3b, v243
	v_exp_f32_e32 v18, v18
	v_exp_f32_e32 v19, v19
	v_exp_f32_e32 v20, v20
	v_exp_f32_e32 v21, v21
	v_add_f32_e32 v239, v239, v14
	v_add_f32_e32 v239, v239, v15
	v_add_f32_e32 v239, v239, v16
	v_add_f32_e32 v239, v239, v17
	v_fmamk_f32 v22, v22, 0x3e38aa3b, v243
	v_fmamk_f32 v23, v23, 0x3e38aa3b, v243
	v_fmamk_f32 v24, v24, 0x3e38aa3b, v243
	v_fmamk_f32 v25, v25, 0x3e38aa3b, v243
	v_exp_f32_e32 v22, v22
	v_exp_f32_e32 v23, v23
	v_exp_f32_e32 v24, v24
	v_exp_f32_e32 v25, v25
	v_add_f32_e32 v239, v239, v18
	v_add_f32_e32 v239, v239, v19
	v_add_f32_e32 v239, v239, v20
	v_add_f32_e32 v239, v239, v21
	v_fmamk_f32 v26, v26, 0x3e38aa3b, v243
	v_fmamk_f32 v27, v27, 0x3e38aa3b, v243
	v_fmamk_f32 v28, v28, 0x3e38aa3b, v243
	v_fmamk_f32 v29, v29, 0x3e38aa3b, v243
	v_exp_f32_e32 v26, v26
	v_exp_f32_e32 v27, v27
	v_exp_f32_e32 v28, v28
	v_exp_f32_e32 v29, v29
	v_add_f32_e32 v239, v239, v22
	v_add_f32_e32 v239, v239, v23
	v_add_f32_e32 v239, v239, v24
	v_add_f32_e32 v239, v239, v25
	v_fmamk_f32 v30, v30, 0x3e38aa3b, v243
	v_fmamk_f32 v31, v31, 0x3e38aa3b, v243
	v_fmamk_f32 v32, v32, 0x3e38aa3b, v243
	v_fmamk_f32 v33, v33, 0x3e38aa3b, v243
	v_exp_f32_e32 v30, v30
	v_exp_f32_e32 v31, v31
	v_exp_f32_e32 v32, v32
	v_exp_f32_e32 v33, v33
	v_add_f32_e32 v239, v239, v26
	v_add_f32_e32 v239, v239, v27
	v_add_f32_e32 v239, v239, v28
	v_add_f32_e32 v239, v239, v29
	v_fmamk_f32 v86, v86, 0x3e38aa3b, v243
	v_fmamk_f32 v87, v87, 0x3e38aa3b, v243
	v_fmamk_f32 v88, v88, 0x3e38aa3b, v243
	v_fmamk_f32 v89, v89, 0x3e38aa3b, v243
	v_exp_f32_e32 v86, v86
	v_exp_f32_e32 v87, v87
	v_exp_f32_e32 v88, v88
	v_exp_f32_e32 v89, v89
	v_add_f32_e32 v239, v239, v30
	v_add_f32_e32 v239, v239, v31
	v_add_f32_e32 v239, v239, v32
	v_add_f32_e32 v239, v239, v33
	s_nop 0
	v_add_f32_e32 v239, v239, v86
	v_add_f32_e32 v239, v239, v87
	v_add_f32_e32 v239, v239, v88
	v_add_f32_e32 v239, v239, v89
	v_xor_b32_e32 v242, 16, v195
	v_lshlrev_b32_e32 v242, 2, v242
	ds_bpermute_b32 v242, v242, v239
	s_waitcnt lgkmcnt(0)
	v_add_f32_e32 v239, v239, v242
	v_xor_b32_e32 v242, 32, v195
	v_lshlrev_b32_e32 v242, 2, v242
	ds_bpermute_b32 v242, v242, v239
	s_waitcnt lgkmcnt(0)
	v_add_f32_e32 v239, v239, v242
	v_sub_f32_e32 v242, v85, v238
	v_mul_f32_e32 v242, 0x3fb8aa3b, v242
	v_exp_f32_e32 v242, v242
	s_nop 0
	v_add_f32_e32 v239, v239, v242
	v_rcp_f32_e32 v244, v239
	v_cvt_pk_bf16_f32 v218, v2, v3
	v_cvt_pk_bf16_f32 v219, v4, v5
	v_cvt_pk_bf16_f32 v220, v6, v7
	v_cvt_pk_bf16_f32 v221, v8, v9
	v_cvt_pk_bf16_f32 v222, v10, v11
	v_cvt_pk_bf16_f32 v223, v12, v13
	v_cvt_pk_bf16_f32 v224, v14, v15
	v_cvt_pk_bf16_f32 v225, v16, v17
	v_cvt_pk_bf16_f32 v226, v18, v19
	v_cvt_pk_bf16_f32 v227, v20, v21
	v_cvt_pk_bf16_f32 v228, v22, v23
	v_cvt_pk_bf16_f32 v229, v24, v25
	v_cvt_pk_bf16_f32 v230, v26, v27
	v_cvt_pk_bf16_f32 v231, v28, v29
	v_cvt_pk_bf16_f32 v232, v30, v31
	v_cvt_pk_bf16_f32 v233, v32, v33
	v_cvt_pk_bf16_f32 v234, v86, v87
	v_cvt_pk_bf16_f32 v235, v88, v89
	v_mov_b32_e32 v236, 0
	v_mov_b32_e32 v237, 0
	ds_read_b64 v[182:183], v245 offset:128
	ds_read_b64 v[184:185], v245 offset:160
	ds_read_b64 v[186:187], v245 offset:8576
	ds_read_b64 v[188:189], v245 offset:8608
	ds_read_b64 v[190:191], v245 offset:17024
	ds_read_b64 v[192:193], v245 offset:17056
	ds_read_b64 v[210:211], v245 offset:25472
	ds_read_b64 v[212:213], v245 offset:25504
	ds_read_b64 v[214:215], v245 offset:192
	ds_read_b64 v[216:217], v245 offset:224
	s_waitcnt lgkmcnt(8)
	v_mfma_f32_16x16x32_bf16 v[142:145], v[182:185], v[218:221], 0
	ds_read_b64 v[182:183], v245 offset:8640
	ds_read_b64 v[184:185], v245 offset:8672
	s_waitcnt lgkmcnt(8)
	v_mfma_f32_16x16x32_bf16 v[146:149], v[186:189], v[218:221], 0
	ds_read_b64 v[186:187], v245 offset:17088
	ds_read_b64 v[188:189], v245 offset:17120
	s_waitcnt lgkmcnt(8)
	v_mfma_f32_16x16x32_bf16 v[150:153], v[190:193], v[218:221], 0
	ds_read_b64 v[190:191], v245 offset:25536
	ds_read_b64 v[192:193], v245 offset:25568
	s_waitcnt lgkmcnt(8)
	v_mfma_f32_16x16x32_bf16 v[154:157], v[210:213], v[218:221], 0
	ds_read_b64 v[210:211], v245 offset:256
	ds_read_b64 v[212:213], v245 offset:288
	s_waitcnt lgkmcnt(8)
	v_mfma_f32_16x16x32_bf16 v[142:145], v[214:217], v[222:225], v[142:145]
	ds_read_b64 v[214:215], v245 offset:8704
	ds_read_b64 v[216:217], v245 offset:8736
	s_waitcnt lgkmcnt(8)
	v_mfma_f32_16x16x32_bf16 v[146:149], v[182:185], v[222:225], v[146:149]
	ds_read_b64 v[182:183], v245 offset:17152
	ds_read_b64 v[184:185], v245 offset:17184
	s_waitcnt lgkmcnt(8)
	v_mfma_f32_16x16x32_bf16 v[150:153], v[186:189], v[222:225], v[150:153]
	ds_read_b64 v[186:187], v245 offset:25600
	ds_read_b64 v[188:189], v245 offset:25632
	s_waitcnt lgkmcnt(8)
	v_mfma_f32_16x16x32_bf16 v[154:157], v[190:193], v[222:225], v[154:157]
	ds_read_b64 v[190:191], v245 offset:320
	ds_read_b64 v[192:193], v245 offset:352
	s_waitcnt lgkmcnt(8)
	v_mfma_f32_16x16x32_bf16 v[142:145], v[210:213], v[226:229], v[142:145]
	ds_read_b64 v[210:211], v245 offset:8768
	ds_read_b64 v[212:213], v245 offset:8800
	s_waitcnt lgkmcnt(8)
	v_mfma_f32_16x16x32_bf16 v[146:149], v[214:217], v[226:229], v[146:149]
	ds_read_b64 v[214:215], v245 offset:17216
	ds_read_b64 v[216:217], v245 offset:17248
	s_waitcnt lgkmcnt(8)
	v_mfma_f32_16x16x32_bf16 v[150:153], v[182:185], v[226:229], v[150:153]
	ds_read_b64 v[182:183], v245 offset:25664
	ds_read_b64 v[184:185], v245 offset:25696
	s_waitcnt lgkmcnt(8)
	v_mfma_f32_16x16x32_bf16 v[154:157], v[186:189], v[226:229], v[154:157]
	ds_read_b64 v[186:187], v245 offset:384
	ds_read_b64 v[188:189], v245 offset:384
	s_waitcnt lgkmcnt(8)
	v_mfma_f32_16x16x32_bf16 v[142:145], v[190:193], v[230:233], v[142:145]
	ds_read_b64 v[190:191], v245 offset:8832
	ds_read_b64 v[192:193], v245 offset:8832
	s_waitcnt lgkmcnt(8)
	v_mfma_f32_16x16x32_bf16 v[146:149], v[210:213], v[230:233], v[146:149]
	ds_read_b64 v[210:211], v245 offset:17280
	ds_read_b64 v[212:213], v245 offset:17280
	s_waitcnt lgkmcnt(8)
	v_mfma_f32_16x16x32_bf16 v[150:153], v[214:217], v[230:233], v[150:153]
	ds_read_b64 v[214:215], v245 offset:25728
	ds_read_b64 v[216:217], v245 offset:25728
	s_waitcnt lgkmcnt(8)
	v_mfma_f32_16x16x32_bf16 v[154:157], v[182:185], v[230:233], v[154:157]
	s_waitcnt lgkmcnt(6)
	v_mfma_f32_16x16x32_bf16 v[142:145], v[186:189], v[234:237], v[142:145]
	s_waitcnt lgkmcnt(4)
	v_mfma_f32_16x16x32_bf16 v[146:149], v[190:193], v[234:237], v[146:149]
	s_waitcnt lgkmcnt(2)
	v_mfma_f32_16x16x32_bf16 v[150:153], v[210:213], v[234:237], v[150:153]
	s_waitcnt lgkmcnt(0)
	v_mfma_f32_16x16x32_bf16 v[154:157], v[214:217], v[234:237], v[154:157]
	s_nop 7
	s_nop 1
	v_mul_f32_e32 v142, v244, v142
	v_mul_f32_e32 v143, v244, v143
	v_mul_f32_e32 v144, v244, v144
	v_mul_f32_e32 v145, v244, v145
	v_mul_f32_e32 v146, v244, v146
	v_mul_f32_e32 v147, v244, v147
	v_mul_f32_e32 v148, v244, v148
	v_mul_f32_e32 v149, v244, v149
	v_cvt_pk_bf16_f32 v240, v142, v143
	v_cvt_pk_bf16_f32 v241, v144, v145
	v_cvt_pk_bf16_f32 v242, v146, v147
	v_cvt_pk_bf16_f32 v243, v148, v149
	global_store_dwordx4 v[246:247], v[240:243], off
	s_nop 1
	v_mul_f32_e32 v150, v244, v150
	v_mul_f32_e32 v151, v244, v151
	v_mul_f32_e32 v152, v244, v152
	v_mul_f32_e32 v153, v244, v153
	v_mul_f32_e32 v154, v244, v154
	v_mul_f32_e32 v155, v244, v155
	v_mul_f32_e32 v156, v244, v156
	v_mul_f32_e32 v157, v244, v157
	v_cvt_pk_bf16_f32 v240, v150, v151
	v_cvt_pk_bf16_f32 v241, v152, v153
	v_cvt_pk_bf16_f32 v242, v154, v155
	v_cvt_pk_bf16_f32 v243, v156, v157
	global_store_dwordx4 v[246:247], v[240:243], off offset:64
	v_lshl_add_u64 v[246:247], v[246:247], 0, s[8:9]
	s_waitcnt vmcnt(2)
	ds_read_b128 v[106:109], v118 offset:11520
	ds_read_b128 v[110:113], v118 offset:11584
	ds_read_b128 v[114:117], v118 offset:13824
	ds_read_b128 v[128:131], v118 offset:13888
	ds_read_b128 v[132:135], v118 offset:16128
	ds_read_b128 v[120:123], v118 offset:16192
	s_waitcnt lgkmcnt(5)
	v_mfma_f32_16x16x32_bf16 v[2:5], v[106:109], v[98:101], 0
	ds_read_b128 v[106:109], v118 offset:18432
	s_waitcnt lgkmcnt(5)
	v_mfma_f32_16x16x32_bf16 v[2:5], v[110:113], v[102:105], v[2:5]
	ds_read_b128 v[110:113], v118 offset:18496
	s_waitcnt lgkmcnt(5)
	v_mfma_f32_16x16x32_bf16 v[6:9], v[114:117], v[98:101], 0
	ds_read_b128 v[114:117], v118 offset:20736
	s_waitcnt lgkmcnt(5)
	v_mfma_f32_16x16x32_bf16 v[6:9], v[128:131], v[102:105], v[6:9]
	ds_read_b128 v[128:131], v118 offset:20800
	s_waitcnt lgkmcnt(5)
	v_mfma_f32_16x16x32_bf16 v[10:13], v[132:135], v[98:101], 0
	ds_read_b128 v[132:135], v118 offset:23040
	s_waitcnt lgkmcnt(5)
	v_mfma_f32_16x16x32_bf16 v[10:13], v[120:123], v[102:105], v[10:13]
	ds_read_b128 v[120:123], v118 offset:23104
	s_waitcnt lgkmcnt(5)
	v_mfma_f32_16x16x32_bf16 v[14:17], v[106:109], v[98:101], 0
	ds_read_b128 v[106:109], v118 offset:25344
	s_waitcnt lgkmcnt(5)
	v_mfma_f32_16x16x32_bf16 v[14:17], v[110:113], v[102:105], v[14:17]
	ds_read_b128 v[110:113], v118 offset:25408
	s_waitcnt lgkmcnt(5)
	v_mfma_f32_16x16x32_bf16 v[18:21], v[114:117], v[98:101], 0
	ds_read_b128 v[114:117], v118 offset:27648
	s_waitcnt lgkmcnt(5)
	v_mfma_f32_16x16x32_bf16 v[18:21], v[128:131], v[102:105], v[18:21]
	ds_read_b128 v[128:131], v118 offset:27712
	s_waitcnt lgkmcnt(5)
	v_mfma_f32_16x16x32_bf16 v[22:25], v[132:135], v[98:101], 0
	ds_read_b128 v[132:135], v118 offset:29952
	s_waitcnt lgkmcnt(5)
	v_mfma_f32_16x16x32_bf16 v[22:25], v[120:123], v[102:105], v[22:25]
	ds_read_b128 v[120:123], v118 offset:30016
	s_waitcnt lgkmcnt(5)
	v_mfma_f32_16x16x32_bf16 v[26:29], v[106:109], v[98:101], 0
	s_waitcnt lgkmcnt(4)
	v_mfma_f32_16x16x32_bf16 v[26:29], v[110:113], v[102:105], v[26:29]
	s_waitcnt lgkmcnt(3)
	v_mfma_f32_16x16x32_bf16 v[30:33], v[114:117], v[98:101], 0
	s_waitcnt lgkmcnt(2)
	v_mfma_f32_16x16x32_bf16 v[30:33], v[128:131], v[102:105], v[30:33]
	s_waitcnt lgkmcnt(1)
	v_mfma_f32_16x16x32_bf16 v[86:89], v[132:135], v[98:101], 0
	s_waitcnt lgkmcnt(0)
	v_mfma_f32_16x16x32_bf16 v[86:89], v[120:123], v[102:105], v[86:89]
	v_lshl_add_u64 v[240:241], v[246:247], 0, s[8:9]
	global_load_dwordx4 v[90:93], v[240:241], off
	global_load_dwordx4 v[94:97], v[240:241], off offset:64
	v_add_u32_e32 v242, 0, v249
	v_cmp_gt_u32_e32 vcc, v242, v248
	s_nop 1
	s_and_b64 vcc, vcc, s[66:67]
	s_nop 0
	v_cndmask_b32_e32 v2, v205, v2, vcc
	v_add_u32_e32 v242, 1, v249
	v_cmp_gt_u32_e32 vcc, v242, v248
	s_nop 1
	s_and_b64 vcc, vcc, s[66:67]
	s_nop 0
	v_cndmask_b32_e32 v3, v205, v3, vcc
	v_add_u32_e32 v242, 2, v249
	v_cmp_gt_u32_e32 vcc, v242, v248
	s_nop 1
	s_and_b64 vcc, vcc, s[66:67]
	s_nop 0
	v_cndmask_b32_e32 v4, v205, v4, vcc
	v_add_u32_e32 v242, 3, v249
	v_cmp_gt_u32_e32 vcc, v242, v248
	s_nop 1
	s_and_b64 vcc, vcc, s[66:67]
	s_nop 0
	v_cndmask_b32_e32 v5, v205, v5, vcc
	v_cndmask_b32_e64 v6, v205, v6, s[66:67]
	v_cndmask_b32_e64 v7, v205, v7, s[66:67]
	v_cndmask_b32_e64 v8, v205, v8, s[66:67]
	v_cndmask_b32_e64 v9, v205, v9, s[66:67]
	v_cndmask_b32_e64 v10, v205, v10, s[66:67]
	v_cndmask_b32_e64 v11, v205, v11, s[66:67]
	v_cndmask_b32_e64 v12, v205, v12, s[66:67]
	v_cndmask_b32_e64 v13, v205, v13, s[66:67]
	v_add_u32_e32 v242, 0, v249
	v_cmp_le_u32_e32 vcc, v242, v248
	s_nop 1
	v_cndmask_b32_e32 v86, v205, v86, vcc
	v_add_u32_e32 v242, 1, v249
	v_cmp_le_u32_e32 vcc, v242, v248
	s_nop 1
	v_cndmask_b32_e32 v87, v205, v87, vcc
	v_add_u32_e32 v242, 2, v249
	v_cmp_le_u32_e32 vcc, v242, v248
	s_nop 1
	v_cndmask_b32_e32 v88, v205, v88, vcc
	v_add_u32_e32 v242, 3, v249
	v_cmp_le_u32_e32 vcc, v242, v248
	s_nop 1
	v_cndmask_b32_e32 v89, v205, v89, vcc
	v_max3_f32 v238, v2, v3, v205
	v_max3_f32 v238, v238, v4, v5
	v_max3_f32 v238, v238, v6, v7
	v_max3_f32 v238, v238, v8, v9
	v_max3_f32 v238, v238, v10, v11
	v_max3_f32 v238, v238, v12, v13
	v_max3_f32 v238, v238, v14, v15
	v_max3_f32 v238, v238, v16, v17
	v_max3_f32 v238, v238, v18, v19
	v_max3_f32 v238, v238, v20, v21
	v_max3_f32 v238, v238, v22, v23
	v_max3_f32 v238, v238, v24, v25
	v_max3_f32 v238, v238, v26, v27
	v_max3_f32 v238, v238, v28, v29
	v_max3_f32 v238, v238, v30, v31
	v_max3_f32 v238, v238, v32, v33
	v_max3_f32 v238, v238, v86, v87
	v_max3_f32 v238, v238, v88, v89
	v_xor_b32_e32 v242, 16, v195
	v_lshlrev_b32_e32 v242, 2, v242
	ds_bpermute_b32 v242, v242, v238
	s_waitcnt lgkmcnt(0)
	v_max_f32_e32 v238, v238, v242
	v_xor_b32_e32 v242, 32, v195
	v_lshlrev_b32_e32 v242, 2, v242
	ds_bpermute_b32 v242, v242, v238
	s_waitcnt lgkmcnt(0)
	v_max_f32_e32 v238, v238, v242
	v_mul_f32_e32 v238, 0x3e000000, v238
	v_max_f32_e32 v238, v238, v85
	v_mul_f32_e32 v243, 0xbfb8aa3b, v238
	v_fmamk_f32 v2, v2, 0x3e38aa3b, v243
	v_fmamk_f32 v3, v3, 0x3e38aa3b, v243
	v_fmamk_f32 v4, v4, 0x3e38aa3b, v243
	v_fmamk_f32 v5, v5, 0x3e38aa3b, v243
	v_exp_f32_e32 v2, v2
	v_exp_f32_e32 v3, v3
	v_exp_f32_e32 v4, v4
	v_exp_f32_e32 v5, v5
	v_fmamk_f32 v6, v6, 0x3e38aa3b, v243
	v_fmamk_f32 v7, v7, 0x3e38aa3b, v243
	v_fmamk_f32 v8, v8, 0x3e38aa3b, v243
	v_fmamk_f32 v9, v9, 0x3e38aa3b, v243
	v_exp_f32_e32 v6, v6
	v_exp_f32_e32 v7, v7
	v_exp_f32_e32 v8, v8
	v_exp_f32_e32 v9, v9
	v_add_f32_e32 v239, 0, v2
	v_add_f32_e32 v239, v239, v3
	v_add_f32_e32 v239, v239, v4
	v_add_f32_e32 v239, v239, v5
	v_fmamk_f32 v10, v10, 0x3e38aa3b, v243
	v_fmamk_f32 v11, v11, 0x3e38aa3b, v243
	v_fmamk_f32 v12, v12, 0x3e38aa3b, v243
	v_fmamk_f32 v13, v13, 0x3e38aa3b, v243
	v_exp_f32_e32 v10, v10
	v_exp_f32_e32 v11, v11
	v_exp_f32_e32 v12, v12
	v_exp_f32_e32 v13, v13
	v_add_f32_e32 v239, v239, v6
	v_add_f32_e32 v239, v239, v7
	v_add_f32_e32 v239, v239, v8
	v_add_f32_e32 v239, v239, v9
	v_fmamk_f32 v14, v14, 0x3e38aa3b, v243
	v_fmamk_f32 v15, v15, 0x3e38aa3b, v243
	v_fmamk_f32 v16, v16, 0x3e38aa3b, v243
	v_fmamk_f32 v17, v17, 0x3e38aa3b, v243
	v_exp_f32_e32 v14, v14
	v_exp_f32_e32 v15, v15
	v_exp_f32_e32 v16, v16
	v_exp_f32_e32 v17, v17
	v_add_f32_e32 v239, v239, v10
	v_add_f32_e32 v239, v239, v11
	v_add_f32_e32 v239, v239, v12
	v_add_f32_e32 v239, v239, v13
	v_fmamk_f32 v18, v18, 0x3e38aa3b, v243
	v_fmamk_f32 v19, v19, 0x3e38aa3b, v243
	v_fmamk_f32 v20, v20, 0x3e38aa3b, v243
	v_fmamk_f32 v21, v21, 0x3e38aa3b, v243
	v_exp_f32_e32 v18, v18
	v_exp_f32_e32 v19, v19
	v_exp_f32_e32 v20, v20
	v_exp_f32_e32 v21, v21
	v_add_f32_e32 v239, v239, v14
	v_add_f32_e32 v239, v239, v15
	v_add_f32_e32 v239, v239, v16
	v_add_f32_e32 v239, v239, v17
	v_fmamk_f32 v22, v22, 0x3e38aa3b, v243
	v_fmamk_f32 v23, v23, 0x3e38aa3b, v243
	v_fmamk_f32 v24, v24, 0x3e38aa3b, v243
	v_fmamk_f32 v25, v25, 0x3e38aa3b, v243
	v_exp_f32_e32 v22, v22
	v_exp_f32_e32 v23, v23
	v_exp_f32_e32 v24, v24
	v_exp_f32_e32 v25, v25
	v_add_f32_e32 v239, v239, v18
	v_add_f32_e32 v239, v239, v19
	v_add_f32_e32 v239, v239, v20
	v_add_f32_e32 v239, v239, v21
	v_fmamk_f32 v26, v26, 0x3e38aa3b, v243
	v_fmamk_f32 v27, v27, 0x3e38aa3b, v243
	v_fmamk_f32 v28, v28, 0x3e38aa3b, v243
	v_fmamk_f32 v29, v29, 0x3e38aa3b, v243
	v_exp_f32_e32 v26, v26
	v_exp_f32_e32 v27, v27
	v_exp_f32_e32 v28, v28
	v_exp_f32_e32 v29, v29
	v_add_f32_e32 v239, v239, v22
	v_add_f32_e32 v239, v239, v23
	v_add_f32_e32 v239, v239, v24
	v_add_f32_e32 v239, v239, v25
	v_fmamk_f32 v30, v30, 0x3e38aa3b, v243
	v_fmamk_f32 v31, v31, 0x3e38aa3b, v243
	v_fmamk_f32 v32, v32, 0x3e38aa3b, v243
	v_fmamk_f32 v33, v33, 0x3e38aa3b, v243
	v_exp_f32_e32 v30, v30
	v_exp_f32_e32 v31, v31
	v_exp_f32_e32 v32, v32
	v_exp_f32_e32 v33, v33
	v_add_f32_e32 v239, v239, v26
	v_add_f32_e32 v239, v239, v27
	v_add_f32_e32 v239, v239, v28
	v_add_f32_e32 v239, v239, v29
	v_fmamk_f32 v86, v86, 0x3e38aa3b, v243
	v_fmamk_f32 v87, v87, 0x3e38aa3b, v243
	v_fmamk_f32 v88, v88, 0x3e38aa3b, v243
	v_fmamk_f32 v89, v89, 0x3e38aa3b, v243
	v_exp_f32_e32 v86, v86
	v_exp_f32_e32 v87, v87
	v_exp_f32_e32 v88, v88
	v_exp_f32_e32 v89, v89
	v_add_f32_e32 v239, v239, v30
	v_add_f32_e32 v239, v239, v31
	v_add_f32_e32 v239, v239, v32
	v_add_f32_e32 v239, v239, v33
	s_nop 0
	v_add_f32_e32 v239, v239, v86
	v_add_f32_e32 v239, v239, v87
	v_add_f32_e32 v239, v239, v88
	v_add_f32_e32 v239, v239, v89
	v_xor_b32_e32 v242, 16, v195
	v_lshlrev_b32_e32 v242, 2, v242
	ds_bpermute_b32 v242, v242, v239
	s_waitcnt lgkmcnt(0)
	v_add_f32_e32 v239, v239, v242
	v_xor_b32_e32 v242, 32, v195
	v_lshlrev_b32_e32 v242, 2, v242
	ds_bpermute_b32 v242, v242, v239
	s_waitcnt lgkmcnt(0)
	v_add_f32_e32 v239, v239, v242
	v_sub_f32_e32 v242, v85, v238
	v_mul_f32_e32 v242, 0x3fb8aa3b, v242
	v_exp_f32_e32 v242, v242
	s_nop 0
	v_add_f32_e32 v239, v239, v242
	v_rcp_f32_e32 v244, v239
	v_cvt_pk_bf16_f32 v218, v2, v3
	v_cvt_pk_bf16_f32 v219, v4, v5
	v_cvt_pk_bf16_f32 v220, v6, v7
	v_cvt_pk_bf16_f32 v221, v8, v9
	v_cvt_pk_bf16_f32 v222, v10, v11
	v_cvt_pk_bf16_f32 v223, v12, v13
	v_cvt_pk_bf16_f32 v224, v14, v15
	v_cvt_pk_bf16_f32 v225, v16, v17
	v_cvt_pk_bf16_f32 v226, v18, v19
	v_cvt_pk_bf16_f32 v227, v20, v21
	v_cvt_pk_bf16_f32 v228, v22, v23
	v_cvt_pk_bf16_f32 v229, v24, v25
	v_cvt_pk_bf16_f32 v230, v26, v27
	v_cvt_pk_bf16_f32 v231, v28, v29
	v_cvt_pk_bf16_f32 v232, v30, v31
	v_cvt_pk_bf16_f32 v233, v32, v33
	v_cvt_pk_bf16_f32 v234, v86, v87
	v_cvt_pk_bf16_f32 v235, v88, v89
	v_mov_b32_e32 v236, 0
	v_mov_b32_e32 v237, 0
	ds_read_b64 v[182:183], v245 offset:160
	ds_read_b64 v[184:185], v245 offset:192
	ds_read_b64 v[186:187], v245 offset:8608
	ds_read_b64 v[188:189], v245 offset:8640
	ds_read_b64 v[190:191], v245 offset:17056
	ds_read_b64 v[192:193], v245 offset:17088
	ds_read_b64 v[210:211], v245 offset:25504
	ds_read_b64 v[212:213], v245 offset:25536
	ds_read_b64 v[214:215], v245 offset:224
	ds_read_b64 v[216:217], v245 offset:256
	s_waitcnt lgkmcnt(8)
	v_mfma_f32_16x16x32_bf16 v[142:145], v[182:185], v[218:221], 0
	ds_read_b64 v[182:183], v245 offset:8672
	ds_read_b64 v[184:185], v245 offset:8704
	s_waitcnt lgkmcnt(8)
	v_mfma_f32_16x16x32_bf16 v[146:149], v[186:189], v[218:221], 0
	ds_read_b64 v[186:187], v245 offset:17120
	ds_read_b64 v[188:189], v245 offset:17152
	s_waitcnt lgkmcnt(8)
	v_mfma_f32_16x16x32_bf16 v[150:153], v[190:193], v[218:221], 0
	ds_read_b64 v[190:191], v245 offset:25568
	ds_read_b64 v[192:193], v245 offset:25600
	s_waitcnt lgkmcnt(8)
	v_mfma_f32_16x16x32_bf16 v[154:157], v[210:213], v[218:221], 0
	ds_read_b64 v[210:211], v245 offset:288
	ds_read_b64 v[212:213], v245 offset:320
	s_waitcnt lgkmcnt(8)
	v_mfma_f32_16x16x32_bf16 v[142:145], v[214:217], v[222:225], v[142:145]
	ds_read_b64 v[214:215], v245 offset:8736
	ds_read_b64 v[216:217], v245 offset:8768
	s_waitcnt lgkmcnt(8)
	v_mfma_f32_16x16x32_bf16 v[146:149], v[182:185], v[222:225], v[146:149]
	ds_read_b64 v[182:183], v245 offset:17184
	ds_read_b64 v[184:185], v245 offset:17216
	s_waitcnt lgkmcnt(8)
	v_mfma_f32_16x16x32_bf16 v[150:153], v[186:189], v[222:225], v[150:153]
	ds_read_b64 v[186:187], v245 offset:25632
	ds_read_b64 v[188:189], v245 offset:25664
	s_waitcnt lgkmcnt(8)
	v_mfma_f32_16x16x32_bf16 v[154:157], v[190:193], v[222:225], v[154:157]
	ds_read_b64 v[190:191], v245 offset:352
	ds_read_b64 v[192:193], v245 offset:384
	s_waitcnt lgkmcnt(8)
	v_mfma_f32_16x16x32_bf16 v[142:145], v[210:213], v[226:229], v[142:145]
	ds_read_b64 v[210:211], v245 offset:8800
	ds_read_b64 v[212:213], v245 offset:8832
	s_waitcnt lgkmcnt(8)
	v_mfma_f32_16x16x32_bf16 v[146:149], v[214:217], v[226:229], v[146:149]
	ds_read_b64 v[214:215], v245 offset:17248
	ds_read_b64 v[216:217], v245 offset:17280
	s_waitcnt lgkmcnt(8)
	v_mfma_f32_16x16x32_bf16 v[150:153], v[182:185], v[226:229], v[150:153]
	ds_read_b64 v[182:183], v245 offset:25696
	ds_read_b64 v[184:185], v245 offset:25728
	s_waitcnt lgkmcnt(8)
	v_mfma_f32_16x16x32_bf16 v[154:157], v[186:189], v[226:229], v[154:157]
	ds_read_b64 v[186:187], v245 offset:416
	ds_read_b64 v[188:189], v245 offset:416
	s_waitcnt lgkmcnt(8)
	v_mfma_f32_16x16x32_bf16 v[142:145], v[190:193], v[230:233], v[142:145]
	ds_read_b64 v[190:191], v245 offset:8864
	ds_read_b64 v[192:193], v245 offset:8864
	s_waitcnt lgkmcnt(8)
	v_mfma_f32_16x16x32_bf16 v[146:149], v[210:213], v[230:233], v[146:149]
	ds_read_b64 v[210:211], v245 offset:17312
	ds_read_b64 v[212:213], v245 offset:17312
	s_waitcnt lgkmcnt(8)
	v_mfma_f32_16x16x32_bf16 v[150:153], v[214:217], v[230:233], v[150:153]
	ds_read_b64 v[214:215], v245 offset:25760
	ds_read_b64 v[216:217], v245 offset:25760
	s_waitcnt lgkmcnt(8)
	v_mfma_f32_16x16x32_bf16 v[154:157], v[182:185], v[230:233], v[154:157]
	s_waitcnt lgkmcnt(6)
	v_mfma_f32_16x16x32_bf16 v[142:145], v[186:189], v[234:237], v[142:145]
	s_waitcnt lgkmcnt(4)
	v_mfma_f32_16x16x32_bf16 v[146:149], v[190:193], v[234:237], v[146:149]
	s_waitcnt lgkmcnt(2)
	v_mfma_f32_16x16x32_bf16 v[150:153], v[210:213], v[234:237], v[150:153]
	s_waitcnt lgkmcnt(0)
	v_mfma_f32_16x16x32_bf16 v[154:157], v[214:217], v[234:237], v[154:157]
	s_nop 7
	s_nop 1
	v_mul_f32_e32 v142, v244, v142
	v_mul_f32_e32 v143, v244, v143
	v_mul_f32_e32 v144, v244, v144
	v_mul_f32_e32 v145, v244, v145
	v_mul_f32_e32 v146, v244, v146
	v_mul_f32_e32 v147, v244, v147
	v_mul_f32_e32 v148, v244, v148
	v_mul_f32_e32 v149, v244, v149
	v_cvt_pk_bf16_f32 v240, v142, v143
	v_cvt_pk_bf16_f32 v241, v144, v145
	v_cvt_pk_bf16_f32 v242, v146, v147
	v_cvt_pk_bf16_f32 v243, v148, v149
	global_store_dwordx4 v[246:247], v[240:243], off
	s_nop 1
	v_mul_f32_e32 v150, v244, v150
	v_mul_f32_e32 v151, v244, v151
	v_mul_f32_e32 v152, v244, v152
	v_mul_f32_e32 v153, v244, v153
	v_mul_f32_e32 v154, v244, v154
	v_mul_f32_e32 v155, v244, v155
	v_mul_f32_e32 v156, v244, v156
	v_mul_f32_e32 v157, v244, v157
	v_cvt_pk_bf16_f32 v240, v150, v151
	v_cvt_pk_bf16_f32 v241, v152, v153
	v_cvt_pk_bf16_f32 v242, v154, v155
	v_cvt_pk_bf16_f32 v243, v156, v157
	global_store_dwordx4 v[246:247], v[240:243], off offset:64
	v_lshl_add_u64 v[246:247], v[246:247], 0, s[8:9]
	s_waitcnt vmcnt(2)
	ds_read_b128 v[106:109], v118 offset:13824
	ds_read_b128 v[110:113], v118 offset:13888
	ds_read_b128 v[114:117], v118 offset:16128
	ds_read_b128 v[128:131], v118 offset:16192
	ds_read_b128 v[132:135], v118 offset:18432
	ds_read_b128 v[120:123], v118 offset:18496
	s_waitcnt lgkmcnt(5)
	v_mfma_f32_16x16x32_bf16 v[2:5], v[106:109], v[90:93], 0
	ds_read_b128 v[106:109], v118 offset:20736
	s_waitcnt lgkmcnt(5)
	v_mfma_f32_16x16x32_bf16 v[2:5], v[110:113], v[94:97], v[2:5]
	ds_read_b128 v[110:113], v118 offset:20800
	s_waitcnt lgkmcnt(5)
	v_mfma_f32_16x16x32_bf16 v[6:9], v[114:117], v[90:93], 0
	ds_read_b128 v[114:117], v118 offset:23040
	s_waitcnt lgkmcnt(5)
	v_mfma_f32_16x16x32_bf16 v[6:9], v[128:131], v[94:97], v[6:9]
	ds_read_b128 v[128:131], v118 offset:23104
	s_waitcnt lgkmcnt(5)
	v_mfma_f32_16x16x32_bf16 v[10:13], v[132:135], v[90:93], 0
	ds_read_b128 v[132:135], v118 offset:25344
	s_waitcnt lgkmcnt(5)
	v_mfma_f32_16x16x32_bf16 v[10:13], v[120:123], v[94:97], v[10:13]
	ds_read_b128 v[120:123], v118 offset:25408
	s_waitcnt lgkmcnt(5)
	v_mfma_f32_16x16x32_bf16 v[14:17], v[106:109], v[90:93], 0
	ds_read_b128 v[106:109], v118 offset:27648
	s_waitcnt lgkmcnt(5)
	v_mfma_f32_16x16x32_bf16 v[14:17], v[110:113], v[94:97], v[14:17]
	ds_read_b128 v[110:113], v118 offset:27712
	s_waitcnt lgkmcnt(5)
	v_mfma_f32_16x16x32_bf16 v[18:21], v[114:117], v[90:93], 0
	ds_read_b128 v[114:117], v118 offset:29952
	s_waitcnt lgkmcnt(5)
	v_mfma_f32_16x16x32_bf16 v[18:21], v[128:131], v[94:97], v[18:21]
	ds_read_b128 v[128:131], v118 offset:30016
	s_waitcnt lgkmcnt(5)
	v_mfma_f32_16x16x32_bf16 v[22:25], v[132:135], v[90:93], 0
	ds_read_b128 v[132:135], v118 offset:32256
	s_waitcnt lgkmcnt(5)
	v_mfma_f32_16x16x32_bf16 v[22:25], v[120:123], v[94:97], v[22:25]
	ds_read_b128 v[120:123], v118 offset:32320
	s_waitcnt lgkmcnt(5)
	v_mfma_f32_16x16x32_bf16 v[26:29], v[106:109], v[90:93], 0
	s_waitcnt lgkmcnt(4)
	v_mfma_f32_16x16x32_bf16 v[26:29], v[110:113], v[94:97], v[26:29]
	s_waitcnt lgkmcnt(3)
	v_mfma_f32_16x16x32_bf16 v[30:33], v[114:117], v[90:93], 0
	s_waitcnt lgkmcnt(2)
	v_mfma_f32_16x16x32_bf16 v[30:33], v[128:131], v[94:97], v[30:33]
	s_waitcnt lgkmcnt(1)
	v_mfma_f32_16x16x32_bf16 v[86:89], v[132:135], v[90:93], 0
	s_waitcnt lgkmcnt(0)
	v_mfma_f32_16x16x32_bf16 v[86:89], v[120:123], v[94:97], v[86:89]
	v_lshl_add_u64 v[240:241], v[246:247], 0, s[8:9]
	global_load_dwordx4 v[98:101], v[240:241], off
	global_load_dwordx4 v[102:105], v[240:241], off offset:64
	v_add_u32_e32 v242, 0, v249
	v_cmp_gt_u32_e32 vcc, v242, v248
	s_nop 1
	s_and_b64 vcc, vcc, s[66:67]
	s_nop 0
	v_cndmask_b32_e32 v2, v205, v2, vcc
	v_add_u32_e32 v242, 1, v249
	v_cmp_gt_u32_e32 vcc, v242, v248
	s_nop 1
	s_and_b64 vcc, vcc, s[66:67]
	s_nop 0
	v_cndmask_b32_e32 v3, v205, v3, vcc
	v_add_u32_e32 v242, 2, v249
	v_cmp_gt_u32_e32 vcc, v242, v248
	s_nop 1
	s_and_b64 vcc, vcc, s[66:67]
	s_nop 0
	v_cndmask_b32_e32 v4, v205, v4, vcc
	v_add_u32_e32 v242, 3, v249
	v_cmp_gt_u32_e32 vcc, v242, v248
	s_nop 1
	s_and_b64 vcc, vcc, s[66:67]
	s_nop 0
	v_cndmask_b32_e32 v5, v205, v5, vcc
	v_cndmask_b32_e64 v6, v205, v6, s[66:67]
	v_cndmask_b32_e64 v7, v205, v7, s[66:67]
	v_cndmask_b32_e64 v8, v205, v8, s[66:67]
	v_cndmask_b32_e64 v9, v205, v9, s[66:67]
	v_add_u32_e32 v242, 0, v249
	v_cmp_le_u32_e32 vcc, v242, v248
	s_nop 1
	v_cndmask_b32_e32 v86, v205, v86, vcc
	v_add_u32_e32 v242, 1, v249
	v_cmp_le_u32_e32 vcc, v242, v248
	s_nop 1
	v_cndmask_b32_e32 v87, v205, v87, vcc
	v_add_u32_e32 v242, 2, v249
	v_cmp_le_u32_e32 vcc, v242, v248
	s_nop 1
	v_cndmask_b32_e32 v88, v205, v88, vcc
	v_add_u32_e32 v242, 3, v249
	v_cmp_le_u32_e32 vcc, v242, v248
	s_nop 1
	v_cndmask_b32_e32 v89, v205, v89, vcc
	v_max3_f32 v238, v2, v3, v205
	v_max3_f32 v238, v238, v4, v5
	v_max3_f32 v238, v238, v6, v7
	v_max3_f32 v238, v238, v8, v9
	v_max3_f32 v238, v238, v10, v11
	v_max3_f32 v238, v238, v12, v13
	v_max3_f32 v238, v238, v14, v15
	v_max3_f32 v238, v238, v16, v17
	v_max3_f32 v238, v238, v18, v19
	v_max3_f32 v238, v238, v20, v21
	v_max3_f32 v238, v238, v22, v23
	v_max3_f32 v238, v238, v24, v25
	v_max3_f32 v238, v238, v26, v27
	v_max3_f32 v238, v238, v28, v29
	v_max3_f32 v238, v238, v30, v31
	v_max3_f32 v238, v238, v32, v33
	v_max3_f32 v238, v238, v86, v87
	v_max3_f32 v238, v238, v88, v89
	v_xor_b32_e32 v242, 16, v195
	v_lshlrev_b32_e32 v242, 2, v242
	ds_bpermute_b32 v242, v242, v238
	s_waitcnt lgkmcnt(0)
	v_max_f32_e32 v238, v238, v242
	v_xor_b32_e32 v242, 32, v195
	v_lshlrev_b32_e32 v242, 2, v242
	ds_bpermute_b32 v242, v242, v238
	s_waitcnt lgkmcnt(0)
	v_max_f32_e32 v238, v238, v242
	v_mul_f32_e32 v238, 0x3e000000, v238
	v_max_f32_e32 v238, v238, v85
	v_mul_f32_e32 v243, 0xbfb8aa3b, v238
	v_fmamk_f32 v2, v2, 0x3e38aa3b, v243
	v_fmamk_f32 v3, v3, 0x3e38aa3b, v243
	v_fmamk_f32 v4, v4, 0x3e38aa3b, v243
	v_fmamk_f32 v5, v5, 0x3e38aa3b, v243
	v_exp_f32_e32 v2, v2
	v_exp_f32_e32 v3, v3
	v_exp_f32_e32 v4, v4
	v_exp_f32_e32 v5, v5
	v_fmamk_f32 v6, v6, 0x3e38aa3b, v243
	v_fmamk_f32 v7, v7, 0x3e38aa3b, v243
	v_fmamk_f32 v8, v8, 0x3e38aa3b, v243
	v_fmamk_f32 v9, v9, 0x3e38aa3b, v243
	v_exp_f32_e32 v6, v6
	v_exp_f32_e32 v7, v7
	v_exp_f32_e32 v8, v8
	v_exp_f32_e32 v9, v9
	v_add_f32_e32 v239, 0, v2
	v_add_f32_e32 v239, v239, v3
	v_add_f32_e32 v239, v239, v4
	v_add_f32_e32 v239, v239, v5
	v_fmamk_f32 v10, v10, 0x3e38aa3b, v243
	v_fmamk_f32 v11, v11, 0x3e38aa3b, v243
	v_fmamk_f32 v12, v12, 0x3e38aa3b, v243
	v_fmamk_f32 v13, v13, 0x3e38aa3b, v243
	v_exp_f32_e32 v10, v10
	v_exp_f32_e32 v11, v11
	v_exp_f32_e32 v12, v12
	v_exp_f32_e32 v13, v13
	v_add_f32_e32 v239, v239, v6
	v_add_f32_e32 v239, v239, v7
	v_add_f32_e32 v239, v239, v8
	v_add_f32_e32 v239, v239, v9
	v_fmamk_f32 v14, v14, 0x3e38aa3b, v243
	v_fmamk_f32 v15, v15, 0x3e38aa3b, v243
	v_fmamk_f32 v16, v16, 0x3e38aa3b, v243
	v_fmamk_f32 v17, v17, 0x3e38aa3b, v243
	v_exp_f32_e32 v14, v14
	v_exp_f32_e32 v15, v15
	v_exp_f32_e32 v16, v16
	v_exp_f32_e32 v17, v17
	v_add_f32_e32 v239, v239, v10
	v_add_f32_e32 v239, v239, v11
	v_add_f32_e32 v239, v239, v12
	v_add_f32_e32 v239, v239, v13
	v_fmamk_f32 v18, v18, 0x3e38aa3b, v243
	v_fmamk_f32 v19, v19, 0x3e38aa3b, v243
	v_fmamk_f32 v20, v20, 0x3e38aa3b, v243
	v_fmamk_f32 v21, v21, 0x3e38aa3b, v243
	v_exp_f32_e32 v18, v18
	v_exp_f32_e32 v19, v19
	v_exp_f32_e32 v20, v20
	v_exp_f32_e32 v21, v21
	v_add_f32_e32 v239, v239, v14
	v_add_f32_e32 v239, v239, v15
	v_add_f32_e32 v239, v239, v16
	v_add_f32_e32 v239, v239, v17
	v_fmamk_f32 v22, v22, 0x3e38aa3b, v243
	v_fmamk_f32 v23, v23, 0x3e38aa3b, v243
	v_fmamk_f32 v24, v24, 0x3e38aa3b, v243
	v_fmamk_f32 v25, v25, 0x3e38aa3b, v243
	v_exp_f32_e32 v22, v22
	v_exp_f32_e32 v23, v23
	v_exp_f32_e32 v24, v24
	v_exp_f32_e32 v25, v25
	v_add_f32_e32 v239, v239, v18
	v_add_f32_e32 v239, v239, v19
	v_add_f32_e32 v239, v239, v20
	v_add_f32_e32 v239, v239, v21
	v_fmamk_f32 v26, v26, 0x3e38aa3b, v243
	v_fmamk_f32 v27, v27, 0x3e38aa3b, v243
	v_fmamk_f32 v28, v28, 0x3e38aa3b, v243
	v_fmamk_f32 v29, v29, 0x3e38aa3b, v243
	v_exp_f32_e32 v26, v26
	v_exp_f32_e32 v27, v27
	v_exp_f32_e32 v28, v28
	v_exp_f32_e32 v29, v29
	v_add_f32_e32 v239, v239, v22
	v_add_f32_e32 v239, v239, v23
	v_add_f32_e32 v239, v239, v24
	v_add_f32_e32 v239, v239, v25
	v_fmamk_f32 v30, v30, 0x3e38aa3b, v243
	v_fmamk_f32 v31, v31, 0x3e38aa3b, v243
	v_fmamk_f32 v32, v32, 0x3e38aa3b, v243
	v_fmamk_f32 v33, v33, 0x3e38aa3b, v243
	v_exp_f32_e32 v30, v30
	v_exp_f32_e32 v31, v31
	v_exp_f32_e32 v32, v32
	v_exp_f32_e32 v33, v33
	v_add_f32_e32 v239, v239, v26
	v_add_f32_e32 v239, v239, v27
	v_add_f32_e32 v239, v239, v28
	v_add_f32_e32 v239, v239, v29
	v_fmamk_f32 v86, v86, 0x3e38aa3b, v243
	v_fmamk_f32 v87, v87, 0x3e38aa3b, v243
	v_fmamk_f32 v88, v88, 0x3e38aa3b, v243
	v_fmamk_f32 v89, v89, 0x3e38aa3b, v243
	v_exp_f32_e32 v86, v86
	v_exp_f32_e32 v87, v87
	v_exp_f32_e32 v88, v88
	v_exp_f32_e32 v89, v89
	v_add_f32_e32 v239, v239, v30
	v_add_f32_e32 v239, v239, v31
	v_add_f32_e32 v239, v239, v32
	v_add_f32_e32 v239, v239, v33
	s_nop 0
	v_add_f32_e32 v239, v239, v86
	v_add_f32_e32 v239, v239, v87
	v_add_f32_e32 v239, v239, v88
	v_add_f32_e32 v239, v239, v89
	v_xor_b32_e32 v242, 16, v195
	v_lshlrev_b32_e32 v242, 2, v242
	ds_bpermute_b32 v242, v242, v239
	s_waitcnt lgkmcnt(0)
	v_add_f32_e32 v239, v239, v242
	v_xor_b32_e32 v242, 32, v195
	v_lshlrev_b32_e32 v242, 2, v242
	ds_bpermute_b32 v242, v242, v239
	s_waitcnt lgkmcnt(0)
	v_add_f32_e32 v239, v239, v242
	v_sub_f32_e32 v242, v85, v238
	v_mul_f32_e32 v242, 0x3fb8aa3b, v242
	v_exp_f32_e32 v242, v242
	s_nop 0
	v_add_f32_e32 v239, v239, v242
	v_rcp_f32_e32 v244, v239
	v_cvt_pk_bf16_f32 v218, v2, v3
	v_cvt_pk_bf16_f32 v219, v4, v5
	v_cvt_pk_bf16_f32 v220, v6, v7
	v_cvt_pk_bf16_f32 v221, v8, v9
	v_cvt_pk_bf16_f32 v222, v10, v11
	v_cvt_pk_bf16_f32 v223, v12, v13
	v_cvt_pk_bf16_f32 v224, v14, v15
	v_cvt_pk_bf16_f32 v225, v16, v17
	v_cvt_pk_bf16_f32 v226, v18, v19
	v_cvt_pk_bf16_f32 v227, v20, v21
	v_cvt_pk_bf16_f32 v228, v22, v23
	v_cvt_pk_bf16_f32 v229, v24, v25
	v_cvt_pk_bf16_f32 v230, v26, v27
	v_cvt_pk_bf16_f32 v231, v28, v29
	v_cvt_pk_bf16_f32 v232, v30, v31
	v_cvt_pk_bf16_f32 v233, v32, v33
	v_cvt_pk_bf16_f32 v234, v86, v87
	v_cvt_pk_bf16_f32 v235, v88, v89
	v_mov_b32_e32 v236, 0
	v_mov_b32_e32 v237, 0
	ds_read_b64 v[182:183], v245 offset:192
	ds_read_b64 v[184:185], v245 offset:224
	ds_read_b64 v[186:187], v245 offset:8640
	ds_read_b64 v[188:189], v245 offset:8672
	ds_read_b64 v[190:191], v245 offset:17088
	ds_read_b64 v[192:193], v245 offset:17120
	ds_read_b64 v[210:211], v245 offset:25536
	ds_read_b64 v[212:213], v245 offset:25568
	ds_read_b64 v[214:215], v245 offset:256
	ds_read_b64 v[216:217], v245 offset:288
	s_waitcnt lgkmcnt(8)
	v_mfma_f32_16x16x32_bf16 v[142:145], v[182:185], v[218:221], 0
	ds_read_b64 v[182:183], v245 offset:8704
	ds_read_b64 v[184:185], v245 offset:8736
	s_waitcnt lgkmcnt(8)
	v_mfma_f32_16x16x32_bf16 v[146:149], v[186:189], v[218:221], 0
	ds_read_b64 v[186:187], v245 offset:17152
	ds_read_b64 v[188:189], v245 offset:17184
	s_waitcnt lgkmcnt(8)
	v_mfma_f32_16x16x32_bf16 v[150:153], v[190:193], v[218:221], 0
	ds_read_b64 v[190:191], v245 offset:25600
	ds_read_b64 v[192:193], v245 offset:25632
	s_waitcnt lgkmcnt(8)
	v_mfma_f32_16x16x32_bf16 v[154:157], v[210:213], v[218:221], 0
	ds_read_b64 v[210:211], v245 offset:320
	ds_read_b64 v[212:213], v245 offset:352
	s_waitcnt lgkmcnt(8)
	v_mfma_f32_16x16x32_bf16 v[142:145], v[214:217], v[222:225], v[142:145]
	ds_read_b64 v[214:215], v245 offset:8768
	ds_read_b64 v[216:217], v245 offset:8800
	s_waitcnt lgkmcnt(8)
	v_mfma_f32_16x16x32_bf16 v[146:149], v[182:185], v[222:225], v[146:149]
	ds_read_b64 v[182:183], v245 offset:17216
	ds_read_b64 v[184:185], v245 offset:17248
	s_waitcnt lgkmcnt(8)
	v_mfma_f32_16x16x32_bf16 v[150:153], v[186:189], v[222:225], v[150:153]
	ds_read_b64 v[186:187], v245 offset:25664
	ds_read_b64 v[188:189], v245 offset:25696
	s_waitcnt lgkmcnt(8)
	v_mfma_f32_16x16x32_bf16 v[154:157], v[190:193], v[222:225], v[154:157]
	ds_read_b64 v[190:191], v245 offset:384
	ds_read_b64 v[192:193], v245 offset:416
	s_waitcnt lgkmcnt(8)
	v_mfma_f32_16x16x32_bf16 v[142:145], v[210:213], v[226:229], v[142:145]
	ds_read_b64 v[210:211], v245 offset:8832
	ds_read_b64 v[212:213], v245 offset:8864
	s_waitcnt lgkmcnt(8)
	v_mfma_f32_16x16x32_bf16 v[146:149], v[214:217], v[226:229], v[146:149]
	ds_read_b64 v[214:215], v245 offset:17280
	ds_read_b64 v[216:217], v245 offset:17312
	s_waitcnt lgkmcnt(8)
	v_mfma_f32_16x16x32_bf16 v[150:153], v[182:185], v[226:229], v[150:153]
	ds_read_b64 v[182:183], v245 offset:25728
	ds_read_b64 v[184:185], v245 offset:25760
	s_waitcnt lgkmcnt(8)
	v_mfma_f32_16x16x32_bf16 v[154:157], v[186:189], v[226:229], v[154:157]
	ds_read_b64 v[186:187], v245 offset:448
	ds_read_b64 v[188:189], v245 offset:448
	s_waitcnt lgkmcnt(8)
	v_mfma_f32_16x16x32_bf16 v[142:145], v[190:193], v[230:233], v[142:145]
	ds_read_b64 v[190:191], v245 offset:8896
	ds_read_b64 v[192:193], v245 offset:8896
	s_waitcnt lgkmcnt(8)
	v_mfma_f32_16x16x32_bf16 v[146:149], v[210:213], v[230:233], v[146:149]
	ds_read_b64 v[210:211], v245 offset:17344
	ds_read_b64 v[212:213], v245 offset:17344
	s_waitcnt lgkmcnt(8)
	v_mfma_f32_16x16x32_bf16 v[150:153], v[214:217], v[230:233], v[150:153]
	ds_read_b64 v[214:215], v245 offset:25792
	ds_read_b64 v[216:217], v245 offset:25792
	s_waitcnt lgkmcnt(8)
	v_mfma_f32_16x16x32_bf16 v[154:157], v[182:185], v[230:233], v[154:157]
	s_waitcnt lgkmcnt(6)
	v_mfma_f32_16x16x32_bf16 v[142:145], v[186:189], v[234:237], v[142:145]
	s_waitcnt lgkmcnt(4)
	v_mfma_f32_16x16x32_bf16 v[146:149], v[190:193], v[234:237], v[146:149]
	s_waitcnt lgkmcnt(2)
	v_mfma_f32_16x16x32_bf16 v[150:153], v[210:213], v[234:237], v[150:153]
	s_waitcnt lgkmcnt(0)
	v_mfma_f32_16x16x32_bf16 v[154:157], v[214:217], v[234:237], v[154:157]
	s_nop 7
	s_nop 1
	v_mul_f32_e32 v142, v244, v142
	v_mul_f32_e32 v143, v244, v143
	v_mul_f32_e32 v144, v244, v144
	v_mul_f32_e32 v145, v244, v145
	v_mul_f32_e32 v146, v244, v146
	v_mul_f32_e32 v147, v244, v147
	v_mul_f32_e32 v148, v244, v148
	v_mul_f32_e32 v149, v244, v149
	v_cvt_pk_bf16_f32 v240, v142, v143
	v_cvt_pk_bf16_f32 v241, v144, v145
	v_cvt_pk_bf16_f32 v242, v146, v147
	v_cvt_pk_bf16_f32 v243, v148, v149
	global_store_dwordx4 v[246:247], v[240:243], off
	s_nop 1
	v_mul_f32_e32 v150, v244, v150
	v_mul_f32_e32 v151, v244, v151
	v_mul_f32_e32 v152, v244, v152
	v_mul_f32_e32 v153, v244, v153
	v_mul_f32_e32 v154, v244, v154
	v_mul_f32_e32 v155, v244, v155
	v_mul_f32_e32 v156, v244, v156
	v_mul_f32_e32 v157, v244, v157
	v_cvt_pk_bf16_f32 v240, v150, v151
	v_cvt_pk_bf16_f32 v241, v152, v153
	v_cvt_pk_bf16_f32 v242, v154, v155
	v_cvt_pk_bf16_f32 v243, v156, v157
	global_store_dwordx4 v[246:247], v[240:243], off offset:64
	v_lshl_add_u64 v[246:247], v[246:247], 0, s[8:9]
	s_waitcnt vmcnt(2)
	ds_read_b128 v[106:109], v118 offset:16128
	ds_read_b128 v[110:113], v118 offset:16192
	ds_read_b128 v[114:117], v118 offset:18432
	ds_read_b128 v[128:131], v118 offset:18496
	ds_read_b128 v[132:135], v118 offset:20736
	ds_read_b128 v[120:123], v118 offset:20800
	s_waitcnt lgkmcnt(5)
	v_mfma_f32_16x16x32_bf16 v[2:5], v[106:109], v[98:101], 0
	ds_read_b128 v[106:109], v118 offset:23040
	s_waitcnt lgkmcnt(5)
	v_mfma_f32_16x16x32_bf16 v[2:5], v[110:113], v[102:105], v[2:5]
	ds_read_b128 v[110:113], v118 offset:23104
	s_waitcnt lgkmcnt(5)
	v_mfma_f32_16x16x32_bf16 v[6:9], v[114:117], v[98:101], 0
	ds_read_b128 v[114:117], v118 offset:25344
	s_waitcnt lgkmcnt(5)
	v_mfma_f32_16x16x32_bf16 v[6:9], v[128:131], v[102:105], v[6:9]
	ds_read_b128 v[128:131], v118 offset:25408
	s_waitcnt lgkmcnt(5)
	v_mfma_f32_16x16x32_bf16 v[10:13], v[132:135], v[98:101], 0
	ds_read_b128 v[132:135], v118 offset:27648
	s_waitcnt lgkmcnt(5)
	v_mfma_f32_16x16x32_bf16 v[10:13], v[120:123], v[102:105], v[10:13]
	ds_read_b128 v[120:123], v118 offset:27712
	s_waitcnt lgkmcnt(5)
	v_mfma_f32_16x16x32_bf16 v[14:17], v[106:109], v[98:101], 0
	ds_read_b128 v[106:109], v118 offset:29952
	s_waitcnt lgkmcnt(5)
	v_mfma_f32_16x16x32_bf16 v[14:17], v[110:113], v[102:105], v[14:17]
	ds_read_b128 v[110:113], v118 offset:30016
	s_waitcnt lgkmcnt(5)
	v_mfma_f32_16x16x32_bf16 v[18:21], v[114:117], v[98:101], 0
	ds_read_b128 v[114:117], v118 offset:32256
	s_waitcnt lgkmcnt(5)
	v_mfma_f32_16x16x32_bf16 v[18:21], v[128:131], v[102:105], v[18:21]
	ds_read_b128 v[128:131], v118 offset:32320
	s_waitcnt lgkmcnt(5)
	v_mfma_f32_16x16x32_bf16 v[22:25], v[132:135], v[98:101], 0
	ds_read_b128 v[132:135], v118 offset:34560
	s_waitcnt lgkmcnt(5)
	v_mfma_f32_16x16x32_bf16 v[22:25], v[120:123], v[102:105], v[22:25]
	ds_read_b128 v[120:123], v118 offset:34624
	s_waitcnt lgkmcnt(5)
	v_mfma_f32_16x16x32_bf16 v[26:29], v[106:109], v[98:101], 0
	s_waitcnt lgkmcnt(4)
	v_mfma_f32_16x16x32_bf16 v[26:29], v[110:113], v[102:105], v[26:29]
	s_waitcnt lgkmcnt(3)
	v_mfma_f32_16x16x32_bf16 v[30:33], v[114:117], v[98:101], 0
	s_waitcnt lgkmcnt(2)
	v_mfma_f32_16x16x32_bf16 v[30:33], v[128:131], v[102:105], v[30:33]
	s_waitcnt lgkmcnt(1)
	v_mfma_f32_16x16x32_bf16 v[86:89], v[132:135], v[98:101], 0
	s_waitcnt lgkmcnt(0)
	v_mfma_f32_16x16x32_bf16 v[86:89], v[120:123], v[102:105], v[86:89]
	v_add_u32_e32 v242, 0, v249
	v_cmp_gt_u32_e32 vcc, v242, v248
	s_nop 1
	s_and_b64 vcc, vcc, s[66:67]
	s_nop 0
	v_cndmask_b32_e32 v2, v205, v2, vcc
	v_add_u32_e32 v242, 1, v249
	v_cmp_gt_u32_e32 vcc, v242, v248
	s_nop 1
	s_and_b64 vcc, vcc, s[66:67]
	s_nop 0
	v_cndmask_b32_e32 v3, v205, v3, vcc
	v_add_u32_e32 v242, 2, v249
	v_cmp_gt_u32_e32 vcc, v242, v248
	s_nop 1
	s_and_b64 vcc, vcc, s[66:67]
	s_nop 0
	v_cndmask_b32_e32 v4, v205, v4, vcc
	v_add_u32_e32 v242, 3, v249
	v_cmp_gt_u32_e32 vcc, v242, v248
	s_nop 1
	s_and_b64 vcc, vcc, s[66:67]
	s_nop 0
	v_cndmask_b32_e32 v5, v205, v5, vcc
	v_add_u32_e32 v242, 0, v249
	v_cmp_le_u32_e32 vcc, v242, v248
	s_nop 1
	v_cndmask_b32_e32 v86, v205, v86, vcc
	v_add_u32_e32 v242, 1, v249
	v_cmp_le_u32_e32 vcc, v242, v248
	s_nop 1
	v_cndmask_b32_e32 v87, v205, v87, vcc
	v_add_u32_e32 v242, 2, v249
	v_cmp_le_u32_e32 vcc, v242, v248
	s_nop 1
	v_cndmask_b32_e32 v88, v205, v88, vcc
	v_add_u32_e32 v242, 3, v249
	v_cmp_le_u32_e32 vcc, v242, v248
	s_nop 1
	v_cndmask_b32_e32 v89, v205, v89, vcc
	v_max3_f32 v238, v2, v3, v205
	v_max3_f32 v238, v238, v4, v5
	v_max3_f32 v238, v238, v6, v7
	v_max3_f32 v238, v238, v8, v9
	v_max3_f32 v238, v238, v10, v11
	v_max3_f32 v238, v238, v12, v13
	v_max3_f32 v238, v238, v14, v15
	v_max3_f32 v238, v238, v16, v17
	v_max3_f32 v238, v238, v18, v19
	v_max3_f32 v238, v238, v20, v21
	v_max3_f32 v238, v238, v22, v23
	v_max3_f32 v238, v238, v24, v25
	v_max3_f32 v238, v238, v26, v27
	v_max3_f32 v238, v238, v28, v29
	v_max3_f32 v238, v238, v30, v31
	v_max3_f32 v238, v238, v32, v33
	v_max3_f32 v238, v238, v86, v87
	v_max3_f32 v238, v238, v88, v89
	v_xor_b32_e32 v242, 16, v195
	v_lshlrev_b32_e32 v242, 2, v242
	ds_bpermute_b32 v242, v242, v238
	s_waitcnt lgkmcnt(0)
	v_max_f32_e32 v238, v238, v242
	v_xor_b32_e32 v242, 32, v195
	v_lshlrev_b32_e32 v242, 2, v242
	ds_bpermute_b32 v242, v242, v238
	s_waitcnt lgkmcnt(0)
	v_max_f32_e32 v238, v238, v242
	v_mul_f32_e32 v238, 0x3e000000, v238
	v_max_f32_e32 v238, v238, v85
	v_mul_f32_e32 v243, 0xbfb8aa3b, v238
	v_fmamk_f32 v2, v2, 0x3e38aa3b, v243
	v_fmamk_f32 v3, v3, 0x3e38aa3b, v243
	v_fmamk_f32 v4, v4, 0x3e38aa3b, v243
	v_fmamk_f32 v5, v5, 0x3e38aa3b, v243
	v_exp_f32_e32 v2, v2
	v_exp_f32_e32 v3, v3
	v_exp_f32_e32 v4, v4
	v_exp_f32_e32 v5, v5
	v_fmamk_f32 v6, v6, 0x3e38aa3b, v243
	v_fmamk_f32 v7, v7, 0x3e38aa3b, v243
	v_fmamk_f32 v8, v8, 0x3e38aa3b, v243
	v_fmamk_f32 v9, v9, 0x3e38aa3b, v243
	v_exp_f32_e32 v6, v6
	v_exp_f32_e32 v7, v7
	v_exp_f32_e32 v8, v8
	v_exp_f32_e32 v9, v9
	v_add_f32_e32 v239, 0, v2
	v_add_f32_e32 v239, v239, v3
	v_add_f32_e32 v239, v239, v4
	v_add_f32_e32 v239, v239, v5
	v_fmamk_f32 v10, v10, 0x3e38aa3b, v243
	v_fmamk_f32 v11, v11, 0x3e38aa3b, v243
	v_fmamk_f32 v12, v12, 0x3e38aa3b, v243
	v_fmamk_f32 v13, v13, 0x3e38aa3b, v243
	v_exp_f32_e32 v10, v10
	v_exp_f32_e32 v11, v11
	v_exp_f32_e32 v12, v12
	v_exp_f32_e32 v13, v13
	v_add_f32_e32 v239, v239, v6
	v_add_f32_e32 v239, v239, v7
	v_add_f32_e32 v239, v239, v8
	v_add_f32_e32 v239, v239, v9
	v_fmamk_f32 v14, v14, 0x3e38aa3b, v243
	v_fmamk_f32 v15, v15, 0x3e38aa3b, v243
	v_fmamk_f32 v16, v16, 0x3e38aa3b, v243
	v_fmamk_f32 v17, v17, 0x3e38aa3b, v243
	v_exp_f32_e32 v14, v14
	v_exp_f32_e32 v15, v15
	v_exp_f32_e32 v16, v16
	v_exp_f32_e32 v17, v17
	v_add_f32_e32 v239, v239, v10
	v_add_f32_e32 v239, v239, v11
	v_add_f32_e32 v239, v239, v12
	v_add_f32_e32 v239, v239, v13
	v_fmamk_f32 v18, v18, 0x3e38aa3b, v243
	v_fmamk_f32 v19, v19, 0x3e38aa3b, v243
	v_fmamk_f32 v20, v20, 0x3e38aa3b, v243
	v_fmamk_f32 v21, v21, 0x3e38aa3b, v243
	v_exp_f32_e32 v18, v18
	v_exp_f32_e32 v19, v19
	v_exp_f32_e32 v20, v20
	v_exp_f32_e32 v21, v21
	v_add_f32_e32 v239, v239, v14
	v_add_f32_e32 v239, v239, v15
	v_add_f32_e32 v239, v239, v16
	v_add_f32_e32 v239, v239, v17
	v_fmamk_f32 v22, v22, 0x3e38aa3b, v243
	v_fmamk_f32 v23, v23, 0x3e38aa3b, v243
	v_fmamk_f32 v24, v24, 0x3e38aa3b, v243
	v_fmamk_f32 v25, v25, 0x3e38aa3b, v243
	v_exp_f32_e32 v22, v22
	v_exp_f32_e32 v23, v23
	v_exp_f32_e32 v24, v24
	v_exp_f32_e32 v25, v25
	v_add_f32_e32 v239, v239, v18
	v_add_f32_e32 v239, v239, v19
	v_add_f32_e32 v239, v239, v20
	v_add_f32_e32 v239, v239, v21
	v_fmamk_f32 v26, v26, 0x3e38aa3b, v243
	v_fmamk_f32 v27, v27, 0x3e38aa3b, v243
	v_fmamk_f32 v28, v28, 0x3e38aa3b, v243
	v_fmamk_f32 v29, v29, 0x3e38aa3b, v243
	v_exp_f32_e32 v26, v26
	v_exp_f32_e32 v27, v27
	v_exp_f32_e32 v28, v28
	v_exp_f32_e32 v29, v29
	v_add_f32_e32 v239, v239, v22
	v_add_f32_e32 v239, v239, v23
	v_add_f32_e32 v239, v239, v24
	v_add_f32_e32 v239, v239, v25
	v_fmamk_f32 v30, v30, 0x3e38aa3b, v243
	v_fmamk_f32 v31, v31, 0x3e38aa3b, v243
	v_fmamk_f32 v32, v32, 0x3e38aa3b, v243
	v_fmamk_f32 v33, v33, 0x3e38aa3b, v243
	v_exp_f32_e32 v30, v30
	v_exp_f32_e32 v31, v31
	v_exp_f32_e32 v32, v32
	v_exp_f32_e32 v33, v33
	v_add_f32_e32 v239, v239, v26
	v_add_f32_e32 v239, v239, v27
	v_add_f32_e32 v239, v239, v28
	v_add_f32_e32 v239, v239, v29
	v_fmamk_f32 v86, v86, 0x3e38aa3b, v243
	v_fmamk_f32 v87, v87, 0x3e38aa3b, v243
	v_fmamk_f32 v88, v88, 0x3e38aa3b, v243
	v_fmamk_f32 v89, v89, 0x3e38aa3b, v243
	v_exp_f32_e32 v86, v86
	v_exp_f32_e32 v87, v87
	v_exp_f32_e32 v88, v88
	v_exp_f32_e32 v89, v89
	v_add_f32_e32 v239, v239, v30
	v_add_f32_e32 v239, v239, v31
	v_add_f32_e32 v239, v239, v32
	v_add_f32_e32 v239, v239, v33
	s_nop 0
	v_add_f32_e32 v239, v239, v86
	v_add_f32_e32 v239, v239, v87
	v_add_f32_e32 v239, v239, v88
	v_add_f32_e32 v239, v239, v89
	v_xor_b32_e32 v242, 16, v195
	v_lshlrev_b32_e32 v242, 2, v242
	ds_bpermute_b32 v242, v242, v239
	s_waitcnt lgkmcnt(0)
	v_add_f32_e32 v239, v239, v242
	v_xor_b32_e32 v242, 32, v195
	v_lshlrev_b32_e32 v242, 2, v242
	ds_bpermute_b32 v242, v242, v239
	s_waitcnt lgkmcnt(0)
	v_add_f32_e32 v239, v239, v242
	v_sub_f32_e32 v242, v85, v238
	v_mul_f32_e32 v242, 0x3fb8aa3b, v242
	v_exp_f32_e32 v242, v242
	s_nop 0
	v_add_f32_e32 v239, v239, v242
	v_rcp_f32_e32 v244, v239
	v_cvt_pk_bf16_f32 v218, v2, v3
	v_cvt_pk_bf16_f32 v219, v4, v5
	v_cvt_pk_bf16_f32 v220, v6, v7
	v_cvt_pk_bf16_f32 v221, v8, v9
	v_cvt_pk_bf16_f32 v222, v10, v11
	v_cvt_pk_bf16_f32 v223, v12, v13
	v_cvt_pk_bf16_f32 v224, v14, v15
	v_cvt_pk_bf16_f32 v225, v16, v17
	v_cvt_pk_bf16_f32 v226, v18, v19
	v_cvt_pk_bf16_f32 v227, v20, v21
	v_cvt_pk_bf16_f32 v228, v22, v23
	v_cvt_pk_bf16_f32 v229, v24, v25
	v_cvt_pk_bf16_f32 v230, v26, v27
	v_cvt_pk_bf16_f32 v231, v28, v29
	v_cvt_pk_bf16_f32 v232, v30, v31
	v_cvt_pk_bf16_f32 v233, v32, v33
	v_cvt_pk_bf16_f32 v234, v86, v87
	v_cvt_pk_bf16_f32 v235, v88, v89
	v_mov_b32_e32 v236, 0
	v_mov_b32_e32 v237, 0
	ds_read_b64 v[182:183], v245 offset:224
	ds_read_b64 v[184:185], v245 offset:256
	ds_read_b64 v[186:187], v245 offset:8672
	ds_read_b64 v[188:189], v245 offset:8704
	ds_read_b64 v[190:191], v245 offset:17120
	ds_read_b64 v[192:193], v245 offset:17152
	ds_read_b64 v[210:211], v245 offset:25568
	ds_read_b64 v[212:213], v245 offset:25600
	ds_read_b64 v[214:215], v245 offset:288
	ds_read_b64 v[216:217], v245 offset:320
	s_waitcnt lgkmcnt(8)
	v_mfma_f32_16x16x32_bf16 v[142:145], v[182:185], v[218:221], 0
	ds_read_b64 v[182:183], v245 offset:8736
	ds_read_b64 v[184:185], v245 offset:8768
	s_waitcnt lgkmcnt(8)
	v_mfma_f32_16x16x32_bf16 v[146:149], v[186:189], v[218:221], 0
	ds_read_b64 v[186:187], v245 offset:17184
	ds_read_b64 v[188:189], v245 offset:17216
	s_waitcnt lgkmcnt(8)
	v_mfma_f32_16x16x32_bf16 v[150:153], v[190:193], v[218:221], 0
	ds_read_b64 v[190:191], v245 offset:25632
	ds_read_b64 v[192:193], v245 offset:25664
	s_waitcnt lgkmcnt(8)
	v_mfma_f32_16x16x32_bf16 v[154:157], v[210:213], v[218:221], 0
	ds_read_b64 v[210:211], v245 offset:352
	ds_read_b64 v[212:213], v245 offset:384
	s_waitcnt lgkmcnt(8)
	v_mfma_f32_16x16x32_bf16 v[142:145], v[214:217], v[222:225], v[142:145]
	ds_read_b64 v[214:215], v245 offset:8800
	ds_read_b64 v[216:217], v245 offset:8832
	s_waitcnt lgkmcnt(8)
	v_mfma_f32_16x16x32_bf16 v[146:149], v[182:185], v[222:225], v[146:149]
	ds_read_b64 v[182:183], v245 offset:17248
	ds_read_b64 v[184:185], v245 offset:17280
	s_waitcnt lgkmcnt(8)
	v_mfma_f32_16x16x32_bf16 v[150:153], v[186:189], v[222:225], v[150:153]
	ds_read_b64 v[186:187], v245 offset:25696
	ds_read_b64 v[188:189], v245 offset:25728
	s_waitcnt lgkmcnt(8)
	v_mfma_f32_16x16x32_bf16 v[154:157], v[190:193], v[222:225], v[154:157]
	ds_read_b64 v[190:191], v245 offset:416
	ds_read_b64 v[192:193], v245 offset:448
	s_waitcnt lgkmcnt(8)
	v_mfma_f32_16x16x32_bf16 v[142:145], v[210:213], v[226:229], v[142:145]
	ds_read_b64 v[210:211], v245 offset:8864
	ds_read_b64 v[212:213], v245 offset:8896
	s_waitcnt lgkmcnt(8)
	v_mfma_f32_16x16x32_bf16 v[146:149], v[214:217], v[226:229], v[146:149]
	ds_read_b64 v[214:215], v245 offset:17312
	ds_read_b64 v[216:217], v245 offset:17344
	s_waitcnt lgkmcnt(8)
	v_mfma_f32_16x16x32_bf16 v[150:153], v[182:185], v[226:229], v[150:153]
	ds_read_b64 v[182:183], v245 offset:25760
	ds_read_b64 v[184:185], v245 offset:25792
	s_waitcnt lgkmcnt(8)
	v_mfma_f32_16x16x32_bf16 v[154:157], v[186:189], v[226:229], v[154:157]
	ds_read_b64 v[186:187], v245 offset:480
	ds_read_b64 v[188:189], v245 offset:480
	s_waitcnt lgkmcnt(8)
	v_mfma_f32_16x16x32_bf16 v[142:145], v[190:193], v[230:233], v[142:145]
	ds_read_b64 v[190:191], v245 offset:8928
	ds_read_b64 v[192:193], v245 offset:8928
	s_waitcnt lgkmcnt(8)
	v_mfma_f32_16x16x32_bf16 v[146:149], v[210:213], v[230:233], v[146:149]
	ds_read_b64 v[210:211], v245 offset:17376
	ds_read_b64 v[212:213], v245 offset:17376
	s_waitcnt lgkmcnt(8)
	v_mfma_f32_16x16x32_bf16 v[150:153], v[214:217], v[230:233], v[150:153]
	ds_read_b64 v[214:215], v245 offset:25824
	ds_read_b64 v[216:217], v245 offset:25824
	s_waitcnt lgkmcnt(8)
	v_mfma_f32_16x16x32_bf16 v[154:157], v[182:185], v[230:233], v[154:157]
	s_waitcnt lgkmcnt(6)
	v_mfma_f32_16x16x32_bf16 v[142:145], v[186:189], v[234:237], v[142:145]
	s_waitcnt lgkmcnt(4)
	v_mfma_f32_16x16x32_bf16 v[146:149], v[190:193], v[234:237], v[146:149]
	s_waitcnt lgkmcnt(2)
	v_mfma_f32_16x16x32_bf16 v[150:153], v[210:213], v[234:237], v[150:153]
	s_waitcnt lgkmcnt(0)
	v_mfma_f32_16x16x32_bf16 v[154:157], v[214:217], v[234:237], v[154:157]
	s_nop 7
	s_nop 1
	v_mul_f32_e32 v142, v244, v142
	v_mul_f32_e32 v143, v244, v143
	v_mul_f32_e32 v144, v244, v144
	v_mul_f32_e32 v145, v244, v145
	v_mul_f32_e32 v146, v244, v146
	v_mul_f32_e32 v147, v244, v147
	v_mul_f32_e32 v148, v244, v148
	v_mul_f32_e32 v149, v244, v149
	v_cvt_pk_bf16_f32 v240, v142, v143
	v_cvt_pk_bf16_f32 v241, v144, v145
	v_cvt_pk_bf16_f32 v242, v146, v147
	v_cvt_pk_bf16_f32 v243, v148, v149
	global_store_dwordx4 v[246:247], v[240:243], off
	s_nop 1
	v_mul_f32_e32 v150, v244, v150
	v_mul_f32_e32 v151, v244, v151
	v_mul_f32_e32 v152, v244, v152
	v_mul_f32_e32 v153, v244, v153
	v_mul_f32_e32 v154, v244, v154
	v_mul_f32_e32 v155, v244, v155
	v_mul_f32_e32 v156, v244, v156
	v_mul_f32_e32 v157, v244, v157
	v_cvt_pk_bf16_f32 v240, v150, v151
	v_cvt_pk_bf16_f32 v241, v152, v153
	v_cvt_pk_bf16_f32 v242, v154, v155
	v_cvt_pk_bf16_f32 v243, v156, v157
	global_store_dwordx4 v[246:247], v[240:243], off offset:64
	v_cndmask_b32_e64 v30, 0, 1, s[74:75]
	v_cmp_ne_u32_e64 s[38:39], 1, v30
	s_branch .LBB0_140
